# RWKV scan consumer: the independent S*w products fill the gaps of the dependent p chain
# baseline (speedup 1.0000x reference)
.LBB0_1750:
	s_and_b32 s23, s22, 1
	s_mul_i32 s2, s23, 0xc000
	s_add_i32 s2, s2, 0
	v_add_u32_e32 v20, s2, v10
	s_add_i32 s2, s2, s5
	v_lshl_add_u32 v21, v1, 2, s2
	ds_read_b128 v[36:39], v20 offset:0
	ds_read_b128 v[40:43], v20 offset:8192
	ds_read_b64 v[56:57], v21 offset:40960
	ds_read_b128 v[48:51], v20 offset:24576
	ds_read_b128 v[44:47], v20 offset:16384
	ds_read_b128 v[52:55], v20 offset:32768
	s_waitcnt lgkmcnt(0)
	ds_read_b128 v[60:63], v20 offset:256
	ds_read_b128 v[64:67], v20 offset:8448
	ds_read_b64 v[80:81], v21 offset:41216
	ds_read_b128 v[72:75], v20 offset:24832
	ds_read_b128 v[68:71], v20 offset:16640
	v_pk_mul_f32 v[22:23], v[2:3], v[36:37] op_sel:[0,0] op_sel_hi:[1,0]
	v_pk_mul_f32 v[84:85], v[2:3], v[40:41] op_sel:[0,0] op_sel_hi:[1,0]
	v_pk_fma_f32 v[22:23], v[4:5], v[36:37], v[22:23] op_sel:[0,1,0] op_sel_hi:[1,1,1]
	v_pk_mul_f32 v[86:87], v[4:5], v[40:41] op_sel:[0,1] op_sel_hi:[1,1]
	v_pk_fma_f32 v[22:23], v[6:7], v[38:39], v[22:23] op_sel:[0,0,0] op_sel_hi:[1,0,1]
	v_pk_mul_f32 v[88:89], v[6:7], v[42:43] op_sel:[0,0] op_sel_hi:[1,0]
	v_pk_fma_f32 v[22:23], v[8:9], v[38:39], v[22:23] op_sel:[0,1,0] op_sel_hi:[1,1,1]
	v_pk_mul_f32 v[90:91], v[8:9], v[42:43] op_sel:[0,1] op_sel_hi:[1,1]
	ds_read_b128 v[76:79], v20 offset:33024
	v_add_f32_dpp v22, v22, v22 quad_perm:[1,0,3,2] row_mask:0xf bank_mask:0xf
	v_add_f32_dpp v23, v23, v23 quad_perm:[1,0,3,2] row_mask:0xf bank_mask:0xf
	v_pk_fma_f32 v[84:85], v[48:49], v[56:57], v[84:85] op_sel:[0,0,0] op_sel_hi:[0,1,1]
	v_add_f32_dpp v22, v22, v22 quad_perm:[2,3,0,1] row_mask:0xf bank_mask:0xf
	v_add_f32_dpp v23, v23, v23 quad_perm:[2,3,0,1] row_mask:0xf bank_mask:0xf
	v_pk_fma_f32 v[86:87], v[48:49], v[56:57], v[86:87] op_sel:[1,0,0] op_sel_hi:[1,1,1]
	v_add_f32_dpp v22, v22, v22 row_half_mirror row_mask:0xf bank_mask:0xf
	v_add_f32_dpp v23, v23, v23 row_half_mirror row_mask:0xf bank_mask:0xf
	v_pk_fma_f32 v[88:89], v[50:51], v[56:57], v[88:89] op_sel:[0,0,0] op_sel_hi:[0,1,1]
	v_add_f32_dpp v22, v22, v22 row_mirror row_mask:0xf bank_mask:0xf
	v_add_f32_dpp v23, v23, v23 row_mirror row_mask:0xf bank_mask:0xf
	v_pk_fma_f32 v[90:91], v[50:51], v[56:57], v[90:91] op_sel:[1,0,0] op_sel_hi:[1,1,1]
	v_pk_fma_f32 v[2:3], v[44:45], v[22:23], v[84:85] op_sel:[0,0,0] op_sel_hi:[0,1,1] neg_lo:[1,0,0] neg_hi:[1,0,0]
	v_pk_fma_f32 v[4:5], v[44:45], v[22:23], v[86:87] op_sel:[1,0,0] op_sel_hi:[1,1,1] neg_lo:[1,0,0] neg_hi:[1,0,0]
	v_pk_fma_f32 v[6:7], v[46:47], v[22:23], v[88:89] op_sel:[0,0,0] op_sel_hi:[0,1,1] neg_lo:[1,0,0] neg_hi:[1,0,0]
	v_pk_fma_f32 v[8:9], v[46:47], v[22:23], v[90:91] op_sel:[1,0,0] op_sel_hi:[1,1,1] neg_lo:[1,0,0] neg_hi:[1,0,0]
	s_waitcnt lgkmcnt(0)
	ds_read_b128 v[36:39], v20 offset:512
	ds_read_b128 v[40:43], v20 offset:8704
	ds_read_b64 v[56:57], v21 offset:41472
	ds_read_b128 v[48:51], v20 offset:25088
	ds_read_b128 v[44:47], v20 offset:16896
	v_pk_mul_f32 v[22:23], v[2:3], v[60:61] op_sel:[0,0] op_sel_hi:[1,0]
	v_pk_mul_f32 v[24:25], v[2:3], v[52:53] op_sel:[0,0] op_sel_hi:[1,0]
	v_pk_mul_f32 v[84:85], v[2:3], v[64:65] op_sel:[0,0] op_sel_hi:[1,0]
	v_pk_fma_f32 v[22:23], v[4:5], v[60:61], v[22:23] op_sel:[0,1,0] op_sel_hi:[1,1,1]
	v_pk_fma_f32 v[24:25], v[4:5], v[52:53], v[24:25] op_sel:[0,1,0] op_sel_hi:[1,1,1]
	v_pk_mul_f32 v[86:87], v[4:5], v[64:65] op_sel:[0,1] op_sel_hi:[1,1]
	v_pk_fma_f32 v[22:23], v[6:7], v[62:63], v[22:23] op_sel:[0,0,0] op_sel_hi:[1,0,1]
	v_pk_fma_f32 v[24:25], v[6:7], v[54:55], v[24:25] op_sel:[0,0,0] op_sel_hi:[1,0,1]
	v_pk_mul_f32 v[88:89], v[6:7], v[66:67] op_sel:[0,0] op_sel_hi:[1,0]
	v_pk_fma_f32 v[22:23], v[8:9], v[62:63], v[22:23] op_sel:[0,1,0] op_sel_hi:[1,1,1]
	v_pk_fma_f32 v[24:25], v[8:9], v[54:55], v[24:25] op_sel:[0,1,0] op_sel_hi:[1,1,1]
	v_pk_mul_f32 v[90:91], v[8:9], v[66:67] op_sel:[0,1] op_sel_hi:[1,1]
	ds_read_b128 v[52:55], v20 offset:33280
	v_add_f32_dpp v22, v22, v22 quad_perm:[1,0,3,2] row_mask:0xf bank_mask:0xf
	v_add_f32_dpp v23, v23, v23 quad_perm:[1,0,3,2] row_mask:0xf bank_mask:0xf
	v_pk_fma_f32 v[84:85], v[72:73], v[80:81], v[84:85] op_sel:[0,0,0] op_sel_hi:[0,1,1]
	v_add_f32_dpp v22, v22, v22 quad_perm:[2,3,0,1] row_mask:0xf bank_mask:0xf
	v_add_f32_dpp v23, v23, v23 quad_perm:[2,3,0,1] row_mask:0xf bank_mask:0xf
	v_pk_fma_f32 v[86:87], v[72:73], v[80:81], v[86:87] op_sel:[1,0,0] op_sel_hi:[1,1,1]
	v_add_f32_dpp v22, v22, v22 row_half_mirror row_mask:0xf bank_mask:0xf
	v_add_f32_dpp v23, v23, v23 row_half_mirror row_mask:0xf bank_mask:0xf
	v_pk_fma_f32 v[88:89], v[74:75], v[80:81], v[88:89] op_sel:[0,0,0] op_sel_hi:[0,1,1]
	v_add_f32_dpp v22, v22, v22 row_mirror row_mask:0xf bank_mask:0xf
	v_add_f32_dpp v23, v23, v23 row_mirror row_mask:0xf bank_mask:0xf
	v_pk_fma_f32 v[90:91], v[74:75], v[80:81], v[90:91] op_sel:[1,0,0] op_sel_hi:[1,1,1]
	v_pk_fma_f32 v[2:3], v[68:69], v[22:23], v[84:85] op_sel:[0,0,0] op_sel_hi:[0,1,1] neg_lo:[1,0,0] neg_hi:[1,0,0]
	v_pk_fma_f32 v[4:5], v[68:69], v[22:23], v[86:87] op_sel:[1,0,0] op_sel_hi:[1,1,1] neg_lo:[1,0,0] neg_hi:[1,0,0]
	v_pk_fma_f32 v[6:7], v[70:71], v[22:23], v[88:89] op_sel:[0,0,0] op_sel_hi:[0,1,1] neg_lo:[1,0,0] neg_hi:[1,0,0]
	v_pk_fma_f32 v[8:9], v[70:71], v[22:23], v[90:91] op_sel:[1,0,0] op_sel_hi:[1,1,1] neg_lo:[1,0,0] neg_hi:[1,0,0]
	s_waitcnt lgkmcnt(0)
	ds_read_b128 v[60:63], v20 offset:768
	ds_read_b128 v[64:67], v20 offset:8960
	ds_read_b64 v[80:81], v21 offset:41728
	ds_read_b128 v[72:75], v20 offset:25344
	ds_read_b128 v[68:71], v20 offset:17152
	v_pk_mul_f32 v[22:23], v[2:3], v[36:37] op_sel:[0,0] op_sel_hi:[1,0]
	v_pk_mul_f32 v[26:27], v[2:3], v[76:77] op_sel:[0,0] op_sel_hi:[1,0]
	v_pk_mul_f32 v[84:85], v[2:3], v[40:41] op_sel:[0,0] op_sel_hi:[1,0]
	v_pk_fma_f32 v[22:23], v[4:5], v[36:37], v[22:23] op_sel:[0,1,0] op_sel_hi:[1,1,1]
	v_pk_fma_f32 v[26:27], v[4:5], v[76:77], v[26:27] op_sel:[0,1,0] op_sel_hi:[1,1,1]
	v_pk_mul_f32 v[86:87], v[4:5], v[40:41] op_sel:[0,1] op_sel_hi:[1,1]
	v_pk_fma_f32 v[22:23], v[6:7], v[38:39], v[22:23] op_sel:[0,0,0] op_sel_hi:[1,0,1]
	v_pk_fma_f32 v[26:27], v[6:7], v[78:79], v[26:27] op_sel:[0,0,0] op_sel_hi:[1,0,1]
	v_pk_mul_f32 v[88:89], v[6:7], v[42:43] op_sel:[0,0] op_sel_hi:[1,0]
	v_pk_fma_f32 v[22:23], v[8:9], v[38:39], v[22:23] op_sel:[0,1,0] op_sel_hi:[1,1,1]
	v_pk_fma_f32 v[26:27], v[8:9], v[78:79], v[26:27] op_sel:[0,1,0] op_sel_hi:[1,1,1]
	v_pk_mul_f32 v[90:91], v[8:9], v[42:43] op_sel:[0,1] op_sel_hi:[1,1]
	ds_read_b128 v[76:79], v20 offset:33536
	v_add_f32_dpp v22, v22, v22 quad_perm:[1,0,3,2] row_mask:0xf bank_mask:0xf
	v_add_f32_dpp v23, v23, v23 quad_perm:[1,0,3,2] row_mask:0xf bank_mask:0xf
	v_pk_fma_f32 v[84:85], v[48:49], v[56:57], v[84:85] op_sel:[0,0,0] op_sel_hi:[0,1,1]
	v_add_f32_dpp v22, v22, v22 quad_perm:[2,3,0,1] row_mask:0xf bank_mask:0xf
	v_add_f32_dpp v23, v23, v23 quad_perm:[2,3,0,1] row_mask:0xf bank_mask:0xf
	v_pk_fma_f32 v[86:87], v[48:49], v[56:57], v[86:87] op_sel:[1,0,0] op_sel_hi:[1,1,1]
	v_add_f32_dpp v22, v22, v22 row_half_mirror row_mask:0xf bank_mask:0xf
	v_add_f32_dpp v23, v23, v23 row_half_mirror row_mask:0xf bank_mask:0xf
	v_pk_fma_f32 v[88:89], v[50:51], v[56:57], v[88:89] op_sel:[0,0,0] op_sel_hi:[0,1,1]
	v_add_f32_dpp v22, v22, v22 row_mirror row_mask:0xf bank_mask:0xf
	v_add_f32_dpp v23, v23, v23 row_mirror row_mask:0xf bank_mask:0xf
	v_pk_fma_f32 v[90:91], v[50:51], v[56:57], v[90:91] op_sel:[1,0,0] op_sel_hi:[1,1,1]
	v_pk_fma_f32 v[2:3], v[44:45], v[22:23], v[84:85] op_sel:[0,0,0] op_sel_hi:[0,1,1] neg_lo:[1,0,0] neg_hi:[1,0,0]
	v_pk_fma_f32 v[4:5], v[44:45], v[22:23], v[86:87] op_sel:[1,0,0] op_sel_hi:[1,1,1] neg_lo:[1,0,0] neg_hi:[1,0,0]
	v_pk_fma_f32 v[6:7], v[46:47], v[22:23], v[88:89] op_sel:[0,0,0] op_sel_hi:[0,1,1] neg_lo:[1,0,0] neg_hi:[1,0,0]
	v_pk_fma_f32 v[8:9], v[46:47], v[22:23], v[90:91] op_sel:[1,0,0] op_sel_hi:[1,1,1] neg_lo:[1,0,0] neg_hi:[1,0,0]
	s_waitcnt lgkmcnt(0)
	ds_read_b128 v[36:39], v20 offset:1024
	ds_read_b128 v[40:43], v20 offset:9216
	ds_read_b64 v[56:57], v21 offset:41984
	ds_read_b128 v[48:51], v20 offset:25600
	ds_read_b128 v[44:47], v20 offset:17408
	v_pk_mul_f32 v[22:23], v[2:3], v[60:61] op_sel:[0,0] op_sel_hi:[1,0]
	v_pk_mul_f32 v[28:29], v[2:3], v[52:53] op_sel:[0,0] op_sel_hi:[1,0]
	v_pk_mul_f32 v[84:85], v[2:3], v[64:65] op_sel:[0,0] op_sel_hi:[1,0]
	v_pk_fma_f32 v[22:23], v[4:5], v[60:61], v[22:23] op_sel:[0,1,0] op_sel_hi:[1,1,1]
	v_pk_fma_f32 v[28:29], v[4:5], v[52:53], v[28:29] op_sel:[0,1,0] op_sel_hi:[1,1,1]
	v_pk_mul_f32 v[86:87], v[4:5], v[64:65] op_sel:[0,1] op_sel_hi:[1,1]
	v_pk_fma_f32 v[22:23], v[6:7], v[62:63], v[22:23] op_sel:[0,0,0] op_sel_hi:[1,0,1]
	v_pk_fma_f32 v[28:29], v[6:7], v[54:55], v[28:29] op_sel:[0,0,0] op_sel_hi:[1,0,1]
	v_pk_mul_f32 v[88:89], v[6:7], v[66:67] op_sel:[0,0] op_sel_hi:[1,0]
	v_pk_fma_f32 v[22:23], v[8:9], v[62:63], v[22:23] op_sel:[0,1,0] op_sel_hi:[1,1,1]
	v_pk_fma_f32 v[28:29], v[8:9], v[54:55], v[28:29] op_sel:[0,1,0] op_sel_hi:[1,1,1]
	v_pk_mul_f32 v[90:91], v[8:9], v[66:67] op_sel:[0,1] op_sel_hi:[1,1]
	ds_read_b128 v[52:55], v20 offset:33792
	v_add_f32_dpp v24, v24, v24 row_ror:12 row_mask:0xf bank_mask:0x5
	v_add_f32_dpp v25, v25, v25 row_ror:4 row_mask:0xf bank_mask:0xa
	v_add_f32_dpp v22, v22, v22 quad_perm:[1,0,3,2] row_mask:0xf bank_mask:0xf
	v_add_f32_dpp v23, v23, v23 quad_perm:[1,0,3,2] row_mask:0xf bank_mask:0xf
	v_pk_fma_f32 v[84:85], v[72:73], v[80:81], v[84:85] op_sel:[0,0,0] op_sel_hi:[0,1,1]
	v_add_f32_dpp v26, v26, v26 row_ror:12 row_mask:0xf bank_mask:0x5
	v_add_f32_dpp v22, v22, v22 quad_perm:[2,3,0,1] row_mask:0xf bank_mask:0xf
	v_add_f32_dpp v23, v23, v23 quad_perm:[2,3,0,1] row_mask:0xf bank_mask:0xf
	v_pk_fma_f32 v[86:87], v[72:73], v[80:81], v[86:87] op_sel:[1,0,0] op_sel_hi:[1,1,1]
	v_add_f32_dpp v27, v27, v27 row_ror:4 row_mask:0xf bank_mask:0xa
	v_add_f32_dpp v22, v22, v22 row_half_mirror row_mask:0xf bank_mask:0xf
	v_add_f32_dpp v23, v23, v23 row_half_mirror row_mask:0xf bank_mask:0xf
	v_pk_fma_f32 v[88:89], v[74:75], v[80:81], v[88:89] op_sel:[0,0,0] op_sel_hi:[0,1,1]
	v_mov_b32_dpp v24, v25 quad_perm:[0,1,2,3] row_mask:0xf bank_mask:0xa
	v_add_f32_dpp v22, v22, v22 row_mirror row_mask:0xf bank_mask:0xf
	v_add_f32_dpp v23, v23, v23 row_mirror row_mask:0xf bank_mask:0xf
	v_pk_fma_f32 v[90:91], v[74:75], v[80:81], v[90:91] op_sel:[1,0,0] op_sel_hi:[1,1,1]
	v_mov_b32_dpp v26, v27 quad_perm:[0,1,2,3] row_mask:0xf bank_mask:0xa
	v_pk_fma_f32 v[2:3], v[68:69], v[22:23], v[84:85] op_sel:[0,0,0] op_sel_hi:[0,1,1] neg_lo:[1,0,0] neg_hi:[1,0,0]
	v_pk_fma_f32 v[4:5], v[68:69], v[22:23], v[86:87] op_sel:[1,0,0] op_sel_hi:[1,1,1] neg_lo:[1,0,0] neg_hi:[1,0,0]
	v_pk_fma_f32 v[6:7], v[70:71], v[22:23], v[88:89] op_sel:[0,0,0] op_sel_hi:[0,1,1] neg_lo:[1,0,0] neg_hi:[1,0,0]
	v_pk_fma_f32 v[8:9], v[70:71], v[22:23], v[90:91] op_sel:[1,0,0] op_sel_hi:[1,1,1] neg_lo:[1,0,0] neg_hi:[1,0,0]
	s_waitcnt lgkmcnt(0)
	ds_read_b128 v[60:63], v20 offset:1280
	ds_read_b128 v[64:67], v20 offset:9472
	ds_read_b64 v[80:81], v21 offset:42240
	ds_read_b128 v[72:75], v20 offset:25856
	ds_read_b128 v[68:71], v20 offset:17664
	v_pk_mul_f32 v[22:23], v[2:3], v[36:37] op_sel:[0,0] op_sel_hi:[1,0]
	v_pk_mul_f32 v[58:59], v[2:3], v[76:77] op_sel:[0,0] op_sel_hi:[1,0]
	v_pk_mul_f32 v[84:85], v[2:3], v[40:41] op_sel:[0,0] op_sel_hi:[1,0]
	v_pk_fma_f32 v[22:23], v[4:5], v[36:37], v[22:23] op_sel:[0,1,0] op_sel_hi:[1,1,1]
	v_pk_fma_f32 v[58:59], v[4:5], v[76:77], v[58:59] op_sel:[0,1,0] op_sel_hi:[1,1,1]
	v_pk_mul_f32 v[86:87], v[4:5], v[40:41] op_sel:[0,1] op_sel_hi:[1,1]
	v_pk_fma_f32 v[22:23], v[6:7], v[38:39], v[22:23] op_sel:[0,0,0] op_sel_hi:[1,0,1]
	v_pk_fma_f32 v[58:59], v[6:7], v[78:79], v[58:59] op_sel:[0,0,0] op_sel_hi:[1,0,1]
	v_pk_mul_f32 v[88:89], v[6:7], v[42:43] op_sel:[0,0] op_sel_hi:[1,0]
	v_pk_fma_f32 v[22:23], v[8:9], v[38:39], v[22:23] op_sel:[0,1,0] op_sel_hi:[1,1,1]
	v_pk_fma_f32 v[58:59], v[8:9], v[78:79], v[58:59] op_sel:[0,1,0] op_sel_hi:[1,1,1]
	v_pk_mul_f32 v[90:91], v[8:9], v[42:43] op_sel:[0,1] op_sel_hi:[1,1]
	ds_read_b128 v[76:79], v20 offset:34048
	v_add_f32_dpp v24, v24, v24 row_ror:8 row_mask:0xf bank_mask:0x3
	v_add_f32_dpp v26, v26, v26 row_ror:8 row_mask:0xf bank_mask:0xc
	v_add_f32_dpp v22, v22, v22 quad_perm:[1,0,3,2] row_mask:0xf bank_mask:0xf
	v_add_f32_dpp v23, v23, v23 quad_perm:[1,0,3,2] row_mask:0xf bank_mask:0xf
	v_pk_fma_f32 v[84:85], v[48:49], v[56:57], v[84:85] op_sel:[0,0,0] op_sel_hi:[0,1,1]
	v_mov_b32_dpp v24, v26 quad_perm:[0,1,2,3] row_mask:0xf bank_mask:0xc
	v_add_f32_dpp v22, v22, v22 quad_perm:[2,3,0,1] row_mask:0xf bank_mask:0xf
	v_add_f32_dpp v23, v23, v23 quad_perm:[2,3,0,1] row_mask:0xf bank_mask:0xf
	v_pk_fma_f32 v[86:87], v[48:49], v[56:57], v[86:87] op_sel:[1,0,0] op_sel_hi:[1,1,1]
	v_add_f32_dpp v24, v24, v24 quad_perm:[1,0,3,2] row_mask:0xf bank_mask:0xf
	v_add_f32_dpp v22, v22, v22 row_half_mirror row_mask:0xf bank_mask:0xf
	v_add_f32_dpp v23, v23, v23 row_half_mirror row_mask:0xf bank_mask:0xf
	v_pk_fma_f32 v[88:89], v[50:51], v[56:57], v[88:89] op_sel:[0,0,0] op_sel_hi:[0,1,1]
	v_add_f32_dpp v24, v24, v24 quad_perm:[2,3,0,1] row_mask:0xf bank_mask:0xf
	v_add_f32_dpp v22, v22, v22 row_mirror row_mask:0xf bank_mask:0xf
	v_add_f32_dpp v23, v23, v23 row_mirror row_mask:0xf bank_mask:0xf
	v_pk_fma_f32 v[90:91], v[50:51], v[56:57], v[90:91] op_sel:[1,0,0] op_sel_hi:[1,1,1]
	v_cndmask_b32_e64 v30, 0, v24, s[0:1]
	v_pk_fma_f32 v[2:3], v[44:45], v[22:23], v[84:85] op_sel:[0,0,0] op_sel_hi:[0,1,1] neg_lo:[1,0,0] neg_hi:[1,0,0]
	v_pk_fma_f32 v[4:5], v[44:45], v[22:23], v[86:87] op_sel:[1,0,0] op_sel_hi:[1,1,1] neg_lo:[1,0,0] neg_hi:[1,0,0]
	v_pk_fma_f32 v[6:7], v[46:47], v[22:23], v[88:89] op_sel:[0,0,0] op_sel_hi:[0,1,1] neg_lo:[1,0,0] neg_hi:[1,0,0]
	v_pk_fma_f32 v[8:9], v[46:47], v[22:23], v[90:91] op_sel:[1,0,0] op_sel_hi:[1,1,1] neg_lo:[1,0,0] neg_hi:[1,0,0]
	s_waitcnt lgkmcnt(0)
	ds_read_b128 v[36:39], v20 offset:1536
	ds_read_b128 v[40:43], v20 offset:9728
	ds_read_b64 v[56:57], v21 offset:42496
	ds_read_b128 v[48:51], v20 offset:26112
	ds_read_b128 v[44:47], v20 offset:17920
	v_pk_mul_f32 v[22:23], v[2:3], v[60:61] op_sel:[0,0] op_sel_hi:[1,0]
	v_pk_mul_f32 v[24:25], v[2:3], v[52:53] op_sel:[0,0] op_sel_hi:[1,0]
	v_pk_mul_f32 v[84:85], v[2:3], v[64:65] op_sel:[0,0] op_sel_hi:[1,0]
	v_pk_fma_f32 v[22:23], v[4:5], v[60:61], v[22:23] op_sel:[0,1,0] op_sel_hi:[1,1,1]
	v_pk_fma_f32 v[24:25], v[4:5], v[52:53], v[24:25] op_sel:[0,1,0] op_sel_hi:[1,1,1]
	v_pk_mul_f32 v[86:87], v[4:5], v[64:65] op_sel:[0,1] op_sel_hi:[1,1]
	v_pk_fma_f32 v[22:23], v[6:7], v[62:63], v[22:23] op_sel:[0,0,0] op_sel_hi:[1,0,1]
	v_pk_fma_f32 v[24:25], v[6:7], v[54:55], v[24:25] op_sel:[0,0,0] op_sel_hi:[1,0,1]
	v_pk_mul_f32 v[88:89], v[6:7], v[66:67] op_sel:[0,0] op_sel_hi:[1,0]
	v_pk_fma_f32 v[22:23], v[8:9], v[62:63], v[22:23] op_sel:[0,1,0] op_sel_hi:[1,1,1]
	v_pk_fma_f32 v[24:25], v[8:9], v[54:55], v[24:25] op_sel:[0,1,0] op_sel_hi:[1,1,1]
	v_pk_mul_f32 v[90:91], v[8:9], v[66:67] op_sel:[0,1] op_sel_hi:[1,1]
	ds_read_b128 v[52:55], v20 offset:34304
	v_add_f32_dpp v28, v28, v28 row_ror:12 row_mask:0xf bank_mask:0x5
	v_add_f32_dpp v29, v29, v29 row_ror:4 row_mask:0xf bank_mask:0xa
	v_add_f32_dpp v22, v22, v22 quad_perm:[1,0,3,2] row_mask:0xf bank_mask:0xf
	v_add_f32_dpp v23, v23, v23 quad_perm:[1,0,3,2] row_mask:0xf bank_mask:0xf
	v_pk_fma_f32 v[84:85], v[72:73], v[80:81], v[84:85] op_sel:[0,0,0] op_sel_hi:[0,1,1]
	v_add_f32_dpp v58, v58, v58 row_ror:12 row_mask:0xf bank_mask:0x5
	v_add_f32_dpp v22, v22, v22 quad_perm:[2,3,0,1] row_mask:0xf bank_mask:0xf
	v_add_f32_dpp v23, v23, v23 quad_perm:[2,3,0,1] row_mask:0xf bank_mask:0xf
	v_pk_fma_f32 v[86:87], v[72:73], v[80:81], v[86:87] op_sel:[1,0,0] op_sel_hi:[1,1,1]
	v_add_f32_dpp v59, v59, v59 row_ror:4 row_mask:0xf bank_mask:0xa
	v_add_f32_dpp v22, v22, v22 row_half_mirror row_mask:0xf bank_mask:0xf
	v_add_f32_dpp v23, v23, v23 row_half_mirror row_mask:0xf bank_mask:0xf
	v_pk_fma_f32 v[88:89], v[74:75], v[80:81], v[88:89] op_sel:[0,0,0] op_sel_hi:[0,1,1]
	v_mov_b32_dpp v28, v29 quad_perm:[0,1,2,3] row_mask:0xf bank_mask:0xa
	v_add_f32_dpp v22, v22, v22 row_mirror row_mask:0xf bank_mask:0xf
	v_add_f32_dpp v23, v23, v23 row_mirror row_mask:0xf bank_mask:0xf
	v_pk_fma_f32 v[90:91], v[74:75], v[80:81], v[90:91] op_sel:[1,0,0] op_sel_hi:[1,1,1]
	v_mov_b32_dpp v58, v59 quad_perm:[0,1,2,3] row_mask:0xf bank_mask:0xa
	v_pk_fma_f32 v[2:3], v[68:69], v[22:23], v[84:85] op_sel:[0,0,0] op_sel_hi:[0,1,1] neg_lo:[1,0,0] neg_hi:[1,0,0]
	v_pk_fma_f32 v[4:5], v[68:69], v[22:23], v[86:87] op_sel:[1,0,0] op_sel_hi:[1,1,1] neg_lo:[1,0,0] neg_hi:[1,0,0]
	v_pk_fma_f32 v[6:7], v[70:71], v[22:23], v[88:89] op_sel:[0,0,0] op_sel_hi:[0,1,1] neg_lo:[1,0,0] neg_hi:[1,0,0]
	v_pk_fma_f32 v[8:9], v[70:71], v[22:23], v[90:91] op_sel:[1,0,0] op_sel_hi:[1,1,1] neg_lo:[1,0,0] neg_hi:[1,0,0]
	s_waitcnt lgkmcnt(0)
	ds_read_b128 v[60:63], v20 offset:1792
	ds_read_b128 v[64:67], v20 offset:9984
	ds_read_b64 v[80:81], v21 offset:42752
	ds_read_b128 v[72:75], v20 offset:26368
	ds_read_b128 v[68:71], v20 offset:18176
	v_pk_mul_f32 v[22:23], v[2:3], v[36:37] op_sel:[0,0] op_sel_hi:[1,0]
	v_pk_mul_f32 v[26:27], v[2:3], v[76:77] op_sel:[0,0] op_sel_hi:[1,0]
	v_pk_mul_f32 v[84:85], v[2:3], v[40:41] op_sel:[0,0] op_sel_hi:[1,0]
	v_pk_fma_f32 v[22:23], v[4:5], v[36:37], v[22:23] op_sel:[0,1,0] op_sel_hi:[1,1,1]
	v_pk_fma_f32 v[26:27], v[4:5], v[76:77], v[26:27] op_sel:[0,1,0] op_sel_hi:[1,1,1]
	v_pk_mul_f32 v[86:87], v[4:5], v[40:41] op_sel:[0,1] op_sel_hi:[1,1]
	v_pk_fma_f32 v[22:23], v[6:7], v[38:39], v[22:23] op_sel:[0,0,0] op_sel_hi:[1,0,1]
	v_pk_fma_f32 v[26:27], v[6:7], v[78:79], v[26:27] op_sel:[0,0,0] op_sel_hi:[1,0,1]
	v_pk_mul_f32 v[88:89], v[6:7], v[42:43] op_sel:[0,0] op_sel_hi:[1,0]
	v_pk_fma_f32 v[22:23], v[8:9], v[38:39], v[22:23] op_sel:[0,1,0] op_sel_hi:[1,1,1]
	v_pk_fma_f32 v[26:27], v[8:9], v[78:79], v[26:27] op_sel:[0,1,0] op_sel_hi:[1,1,1]
	v_pk_mul_f32 v[90:91], v[8:9], v[42:43] op_sel:[0,1] op_sel_hi:[1,1]
	ds_read_b128 v[76:79], v20 offset:34560
	v_add_f32_dpp v28, v28, v28 row_ror:8 row_mask:0xf bank_mask:0x3
	v_add_f32_dpp v58, v58, v58 row_ror:8 row_mask:0xf bank_mask:0xc
	v_add_f32_dpp v22, v22, v22 quad_perm:[1,0,3,2] row_mask:0xf bank_mask:0xf
	v_add_f32_dpp v23, v23, v23 quad_perm:[1,0,3,2] row_mask:0xf bank_mask:0xf
	v_pk_fma_f32 v[84:85], v[48:49], v[56:57], v[84:85] op_sel:[0,0,0] op_sel_hi:[0,1,1]
	v_mov_b32_dpp v28, v58 quad_perm:[0,1,2,3] row_mask:0xf bank_mask:0xc
	v_add_f32_dpp v22, v22, v22 quad_perm:[2,3,0,1] row_mask:0xf bank_mask:0xf
	v_add_f32_dpp v23, v23, v23 quad_perm:[2,3,0,1] row_mask:0xf bank_mask:0xf
	v_pk_fma_f32 v[86:87], v[48:49], v[56:57], v[86:87] op_sel:[1,0,0] op_sel_hi:[1,1,1]
	v_add_f32_dpp v28, v28, v28 quad_perm:[1,0,3,2] row_mask:0xf bank_mask:0xf
	v_add_f32_dpp v22, v22, v22 row_half_mirror row_mask:0xf bank_mask:0xf
	v_add_f32_dpp v23, v23, v23 row_half_mirror row_mask:0xf bank_mask:0xf
	v_pk_fma_f32 v[88:89], v[50:51], v[56:57], v[88:89] op_sel:[0,0,0] op_sel_hi:[0,1,1]
	v_add_f32_dpp v28, v28, v28 quad_perm:[2,3,0,1] row_mask:0xf bank_mask:0xf
	v_add_f32_dpp v22, v22, v22 row_mirror row_mask:0xf bank_mask:0xf
	v_add_f32_dpp v23, v23, v23 row_mirror row_mask:0xf bank_mask:0xf
	v_pk_fma_f32 v[90:91], v[50:51], v[56:57], v[90:91] op_sel:[1,0,0] op_sel_hi:[1,1,1]
	v_cndmask_b32_e64 v30, v30, v28, s[6:7]
	v_pk_fma_f32 v[2:3], v[44:45], v[22:23], v[84:85] op_sel:[0,0,0] op_sel_hi:[0,1,1] neg_lo:[1,0,0] neg_hi:[1,0,0]
	v_pk_fma_f32 v[4:5], v[44:45], v[22:23], v[86:87] op_sel:[1,0,0] op_sel_hi:[1,1,1] neg_lo:[1,0,0] neg_hi:[1,0,0]
	v_pk_fma_f32 v[6:7], v[46:47], v[22:23], v[88:89] op_sel:[0,0,0] op_sel_hi:[0,1,1] neg_lo:[1,0,0] neg_hi:[1,0,0]
	v_pk_fma_f32 v[8:9], v[46:47], v[22:23], v[90:91] op_sel:[1,0,0] op_sel_hi:[1,1,1] neg_lo:[1,0,0] neg_hi:[1,0,0]
	s_waitcnt lgkmcnt(0)
	ds_read_b128 v[36:39], v20 offset:2048
	ds_read_b128 v[40:43], v20 offset:10240
	ds_read_b64 v[56:57], v21 offset:43008
	ds_read_b128 v[48:51], v20 offset:26624
	ds_read_b128 v[44:47], v20 offset:18432
	v_pk_mul_f32 v[22:23], v[2:3], v[60:61] op_sel:[0,0] op_sel_hi:[1,0]
	v_pk_mul_f32 v[28:29], v[2:3], v[52:53] op_sel:[0,0] op_sel_hi:[1,0]
	v_pk_mul_f32 v[84:85], v[2:3], v[64:65] op_sel:[0,0] op_sel_hi:[1,0]
	v_pk_fma_f32 v[22:23], v[4:5], v[60:61], v[22:23] op_sel:[0,1,0] op_sel_hi:[1,1,1]
	v_pk_fma_f32 v[28:29], v[4:5], v[52:53], v[28:29] op_sel:[0,1,0] op_sel_hi:[1,1,1]
	v_pk_mul_f32 v[86:87], v[4:5], v[64:65] op_sel:[0,1] op_sel_hi:[1,1]
	v_pk_fma_f32 v[22:23], v[6:7], v[62:63], v[22:23] op_sel:[0,0,0] op_sel_hi:[1,0,1]
	v_pk_fma_f32 v[28:29], v[6:7], v[54:55], v[28:29] op_sel:[0,0,0] op_sel_hi:[1,0,1]
	v_pk_mul_f32 v[88:89], v[6:7], v[66:67] op_sel:[0,0] op_sel_hi:[1,0]
	v_pk_fma_f32 v[22:23], v[8:9], v[62:63], v[22:23] op_sel:[0,1,0] op_sel_hi:[1,1,1]
	v_pk_fma_f32 v[28:29], v[8:9], v[54:55], v[28:29] op_sel:[0,1,0] op_sel_hi:[1,1,1]
	v_pk_mul_f32 v[90:91], v[8:9], v[66:67] op_sel:[0,1] op_sel_hi:[1,1]
	ds_read_b128 v[52:55], v20 offset:34816
	v_add_f32_dpp v24, v24, v24 row_ror:12 row_mask:0xf bank_mask:0x5
	v_add_f32_dpp v25, v25, v25 row_ror:4 row_mask:0xf bank_mask:0xa
	v_add_f32_dpp v22, v22, v22 quad_perm:[1,0,3,2] row_mask:0xf bank_mask:0xf
	v_add_f32_dpp v23, v23, v23 quad_perm:[1,0,3,2] row_mask:0xf bank_mask:0xf
	v_pk_fma_f32 v[84:85], v[72:73], v[80:81], v[84:85] op_sel:[0,0,0] op_sel_hi:[0,1,1]
	v_add_f32_dpp v26, v26, v26 row_ror:12 row_mask:0xf bank_mask:0x5
	v_add_f32_dpp v22, v22, v22 quad_perm:[2,3,0,1] row_mask:0xf bank_mask:0xf
	v_add_f32_dpp v23, v23, v23 quad_perm:[2,3,0,1] row_mask:0xf bank_mask:0xf
	v_pk_fma_f32 v[86:87], v[72:73], v[80:81], v[86:87] op_sel:[1,0,0] op_sel_hi:[1,1,1]
	v_add_f32_dpp v27, v27, v27 row_ror:4 row_mask:0xf bank_mask:0xa
	v_add_f32_dpp v22, v22, v22 row_half_mirror row_mask:0xf bank_mask:0xf
	v_add_f32_dpp v23, v23, v23 row_half_mirror row_mask:0xf bank_mask:0xf
	v_pk_fma_f32 v[88:89], v[74:75], v[80:81], v[88:89] op_sel:[0,0,0] op_sel_hi:[0,1,1]
	v_mov_b32_dpp v24, v25 quad_perm:[0,1,2,3] row_mask:0xf bank_mask:0xa
	v_add_f32_dpp v22, v22, v22 row_mirror row_mask:0xf bank_mask:0xf
	v_add_f32_dpp v23, v23, v23 row_mirror row_mask:0xf bank_mask:0xf
	v_pk_fma_f32 v[90:91], v[74:75], v[80:81], v[90:91] op_sel:[1,0,0] op_sel_hi:[1,1,1]
	v_mov_b32_dpp v26, v27 quad_perm:[0,1,2,3] row_mask:0xf bank_mask:0xa
	v_pk_fma_f32 v[2:3], v[68:69], v[22:23], v[84:85] op_sel:[0,0,0] op_sel_hi:[0,1,1] neg_lo:[1,0,0] neg_hi:[1,0,0]
	v_pk_fma_f32 v[4:5], v[68:69], v[22:23], v[86:87] op_sel:[1,0,0] op_sel_hi:[1,1,1] neg_lo:[1,0,0] neg_hi:[1,0,0]
	v_pk_fma_f32 v[6:7], v[70:71], v[22:23], v[88:89] op_sel:[0,0,0] op_sel_hi:[0,1,1] neg_lo:[1,0,0] neg_hi:[1,0,0]
	v_pk_fma_f32 v[8:9], v[70:71], v[22:23], v[90:91] op_sel:[1,0,0] op_sel_hi:[1,1,1] neg_lo:[1,0,0] neg_hi:[1,0,0]
	s_waitcnt lgkmcnt(0)
	ds_read_b128 v[60:63], v20 offset:2304
	ds_read_b128 v[64:67], v20 offset:10496
	ds_read_b64 v[80:81], v21 offset:43264
	ds_read_b128 v[72:75], v20 offset:26880
	ds_read_b128 v[68:71], v20 offset:18688
	v_pk_mul_f32 v[22:23], v[2:3], v[36:37] op_sel:[0,0] op_sel_hi:[1,0]
	v_pk_mul_f32 v[58:59], v[2:3], v[76:77] op_sel:[0,0] op_sel_hi:[1,0]
	v_pk_mul_f32 v[84:85], v[2:3], v[40:41] op_sel:[0,0] op_sel_hi:[1,0]
	v_pk_fma_f32 v[22:23], v[4:5], v[36:37], v[22:23] op_sel:[0,1,0] op_sel_hi:[1,1,1]
	v_pk_fma_f32 v[58:59], v[4:5], v[76:77], v[58:59] op_sel:[0,1,0] op_sel_hi:[1,1,1]
	v_pk_mul_f32 v[86:87], v[4:5], v[40:41] op_sel:[0,1] op_sel_hi:[1,1]
	v_pk_fma_f32 v[22:23], v[6:7], v[38:39], v[22:23] op_sel:[0,0,0] op_sel_hi:[1,0,1]
	v_pk_fma_f32 v[58:59], v[6:7], v[78:79], v[58:59] op_sel:[0,0,0] op_sel_hi:[1,0,1]
	v_pk_mul_f32 v[88:89], v[6:7], v[42:43] op_sel:[0,0] op_sel_hi:[1,0]
	v_pk_fma_f32 v[22:23], v[8:9], v[38:39], v[22:23] op_sel:[0,1,0] op_sel_hi:[1,1,1]
	v_pk_fma_f32 v[58:59], v[8:9], v[78:79], v[58:59] op_sel:[0,1,0] op_sel_hi:[1,1,1]
	v_pk_mul_f32 v[90:91], v[8:9], v[42:43] op_sel:[0,1] op_sel_hi:[1,1]
	ds_read_b128 v[76:79], v20 offset:35072
	v_add_f32_dpp v24, v24, v24 row_ror:8 row_mask:0xf bank_mask:0x3
	v_add_f32_dpp v26, v26, v26 row_ror:8 row_mask:0xf bank_mask:0xc
	v_add_f32_dpp v22, v22, v22 quad_perm:[1,0,3,2] row_mask:0xf bank_mask:0xf
	v_add_f32_dpp v23, v23, v23 quad_perm:[1,0,3,2] row_mask:0xf bank_mask:0xf
	v_pk_fma_f32 v[84:85], v[48:49], v[56:57], v[84:85] op_sel:[0,0,0] op_sel_hi:[0,1,1]
	v_mov_b32_dpp v24, v26 quad_perm:[0,1,2,3] row_mask:0xf bank_mask:0xc
	v_add_f32_dpp v22, v22, v22 quad_perm:[2,3,0,1] row_mask:0xf bank_mask:0xf
	v_add_f32_dpp v23, v23, v23 quad_perm:[2,3,0,1] row_mask:0xf bank_mask:0xf
	v_pk_fma_f32 v[86:87], v[48:49], v[56:57], v[86:87] op_sel:[1,0,0] op_sel_hi:[1,1,1]
	v_add_f32_dpp v24, v24, v24 quad_perm:[1,0,3,2] row_mask:0xf bank_mask:0xf
	v_add_f32_dpp v22, v22, v22 row_half_mirror row_mask:0xf bank_mask:0xf
	v_add_f32_dpp v23, v23, v23 row_half_mirror row_mask:0xf bank_mask:0xf
	v_pk_fma_f32 v[88:89], v[50:51], v[56:57], v[88:89] op_sel:[0,0,0] op_sel_hi:[0,1,1]
	v_add_f32_dpp v24, v24, v24 quad_perm:[2,3,0,1] row_mask:0xf bank_mask:0xf
	v_add_f32_dpp v22, v22, v22 row_mirror row_mask:0xf bank_mask:0xf
	v_add_f32_dpp v23, v23, v23 row_mirror row_mask:0xf bank_mask:0xf
	v_pk_fma_f32 v[90:91], v[50:51], v[56:57], v[90:91] op_sel:[1,0,0] op_sel_hi:[1,1,1]
	v_cndmask_b32_e64 v30, v30, v24, s[8:9]
	v_pk_fma_f32 v[2:3], v[44:45], v[22:23], v[84:85] op_sel:[0,0,0] op_sel_hi:[0,1,1] neg_lo:[1,0,0] neg_hi:[1,0,0]
	v_pk_fma_f32 v[4:5], v[44:45], v[22:23], v[86:87] op_sel:[1,0,0] op_sel_hi:[1,1,1] neg_lo:[1,0,0] neg_hi:[1,0,0]
	v_pk_fma_f32 v[6:7], v[46:47], v[22:23], v[88:89] op_sel:[0,0,0] op_sel_hi:[0,1,1] neg_lo:[1,0,0] neg_hi:[1,0,0]
	v_pk_fma_f32 v[8:9], v[46:47], v[22:23], v[90:91] op_sel:[1,0,0] op_sel_hi:[1,1,1] neg_lo:[1,0,0] neg_hi:[1,0,0]
	s_waitcnt lgkmcnt(0)
	ds_read_b128 v[36:39], v20 offset:2560
	ds_read_b128 v[40:43], v20 offset:10752
	ds_read_b64 v[56:57], v21 offset:43520
	ds_read_b128 v[48:51], v20 offset:27136
	ds_read_b128 v[44:47], v20 offset:18944
	v_pk_mul_f32 v[22:23], v[2:3], v[60:61] op_sel:[0,0] op_sel_hi:[1,0]
	v_pk_mul_f32 v[24:25], v[2:3], v[52:53] op_sel:[0,0] op_sel_hi:[1,0]
	v_pk_mul_f32 v[84:85], v[2:3], v[64:65] op_sel:[0,0] op_sel_hi:[1,0]
	v_pk_fma_f32 v[22:23], v[4:5], v[60:61], v[22:23] op_sel:[0,1,0] op_sel_hi:[1,1,1]
	v_pk_fma_f32 v[24:25], v[4:5], v[52:53], v[24:25] op_sel:[0,1,0] op_sel_hi:[1,1,1]
	v_pk_mul_f32 v[86:87], v[4:5], v[64:65] op_sel:[0,1] op_sel_hi:[1,1]
	v_pk_fma_f32 v[22:23], v[6:7], v[62:63], v[22:23] op_sel:[0,0,0] op_sel_hi:[1,0,1]
	v_pk_fma_f32 v[24:25], v[6:7], v[54:55], v[24:25] op_sel:[0,0,0] op_sel_hi:[1,0,1]
	v_pk_mul_f32 v[88:89], v[6:7], v[66:67] op_sel:[0,0] op_sel_hi:[1,0]
	v_pk_fma_f32 v[22:23], v[8:9], v[62:63], v[22:23] op_sel:[0,1,0] op_sel_hi:[1,1,1]
	v_pk_fma_f32 v[24:25], v[8:9], v[54:55], v[24:25] op_sel:[0,1,0] op_sel_hi:[1,1,1]
	v_pk_mul_f32 v[90:91], v[8:9], v[66:67] op_sel:[0,1] op_sel_hi:[1,1]
	ds_read_b128 v[52:55], v20 offset:35328
	v_add_f32_dpp v28, v28, v28 row_ror:12 row_mask:0xf bank_mask:0x5
	v_add_f32_dpp v29, v29, v29 row_ror:4 row_mask:0xf bank_mask:0xa
	v_add_f32_dpp v22, v22, v22 quad_perm:[1,0,3,2] row_mask:0xf bank_mask:0xf
	v_add_f32_dpp v23, v23, v23 quad_perm:[1,0,3,2] row_mask:0xf bank_mask:0xf
	v_pk_fma_f32 v[84:85], v[72:73], v[80:81], v[84:85] op_sel:[0,0,0] op_sel_hi:[0,1,1]
	v_add_f32_dpp v58, v58, v58 row_ror:12 row_mask:0xf bank_mask:0x5
	v_add_f32_dpp v22, v22, v22 quad_perm:[2,3,0,1] row_mask:0xf bank_mask:0xf
	v_add_f32_dpp v23, v23, v23 quad_perm:[2,3,0,1] row_mask:0xf bank_mask:0xf
	v_pk_fma_f32 v[86:87], v[72:73], v[80:81], v[86:87] op_sel:[1,0,0] op_sel_hi:[1,1,1]
	v_add_f32_dpp v59, v59, v59 row_ror:4 row_mask:0xf bank_mask:0xa
	v_add_f32_dpp v22, v22, v22 row_half_mirror row_mask:0xf bank_mask:0xf
	v_add_f32_dpp v23, v23, v23 row_half_mirror row_mask:0xf bank_mask:0xf
	v_pk_fma_f32 v[88:89], v[74:75], v[80:81], v[88:89] op_sel:[0,0,0] op_sel_hi:[0,1,1]
	v_mov_b32_dpp v28, v29 quad_perm:[0,1,2,3] row_mask:0xf bank_mask:0xa
	v_add_f32_dpp v22, v22, v22 row_mirror row_mask:0xf bank_mask:0xf
	v_add_f32_dpp v23, v23, v23 row_mirror row_mask:0xf bank_mask:0xf
	v_pk_fma_f32 v[90:91], v[74:75], v[80:81], v[90:91] op_sel:[1,0,0] op_sel_hi:[1,1,1]
	v_mov_b32_dpp v58, v59 quad_perm:[0,1,2,3] row_mask:0xf bank_mask:0xa
	v_pk_fma_f32 v[2:3], v[68:69], v[22:23], v[84:85] op_sel:[0,0,0] op_sel_hi:[0,1,1] neg_lo:[1,0,0] neg_hi:[1,0,0]
	v_pk_fma_f32 v[4:5], v[68:69], v[22:23], v[86:87] op_sel:[1,0,0] op_sel_hi:[1,1,1] neg_lo:[1,0,0] neg_hi:[1,0,0]
	v_pk_fma_f32 v[6:7], v[70:71], v[22:23], v[88:89] op_sel:[0,0,0] op_sel_hi:[0,1,1] neg_lo:[1,0,0] neg_hi:[1,0,0]
	v_pk_fma_f32 v[8:9], v[70:71], v[22:23], v[90:91] op_sel:[1,0,0] op_sel_hi:[1,1,1] neg_lo:[1,0,0] neg_hi:[1,0,0]
	s_waitcnt lgkmcnt(0)
	ds_read_b128 v[60:63], v20 offset:2816
	ds_read_b128 v[64:67], v20 offset:11008
	ds_read_b64 v[80:81], v21 offset:43776
	ds_read_b128 v[72:75], v20 offset:27392
	ds_read_b128 v[68:71], v20 offset:19200
	v_pk_mul_f32 v[22:23], v[2:3], v[36:37] op_sel:[0,0] op_sel_hi:[1,0]
	v_pk_mul_f32 v[26:27], v[2:3], v[76:77] op_sel:[0,0] op_sel_hi:[1,0]
	v_pk_mul_f32 v[84:85], v[2:3], v[40:41] op_sel:[0,0] op_sel_hi:[1,0]
	v_pk_fma_f32 v[22:23], v[4:5], v[36:37], v[22:23] op_sel:[0,1,0] op_sel_hi:[1,1,1]
	v_pk_fma_f32 v[26:27], v[4:5], v[76:77], v[26:27] op_sel:[0,1,0] op_sel_hi:[1,1,1]
	v_pk_mul_f32 v[86:87], v[4:5], v[40:41] op_sel:[0,1] op_sel_hi:[1,1]
	v_pk_fma_f32 v[22:23], v[6:7], v[38:39], v[22:23] op_sel:[0,0,0] op_sel_hi:[1,0,1]
	v_pk_fma_f32 v[26:27], v[6:7], v[78:79], v[26:27] op_sel:[0,0,0] op_sel_hi:[1,0,1]
	v_pk_mul_f32 v[88:89], v[6:7], v[42:43] op_sel:[0,0] op_sel_hi:[1,0]
	v_pk_fma_f32 v[22:23], v[8:9], v[38:39], v[22:23] op_sel:[0,1,0] op_sel_hi:[1,1,1]
	v_pk_fma_f32 v[26:27], v[8:9], v[78:79], v[26:27] op_sel:[0,1,0] op_sel_hi:[1,1,1]
	v_pk_mul_f32 v[90:91], v[8:9], v[42:43] op_sel:[0,1] op_sel_hi:[1,1]
	ds_read_b128 v[76:79], v20 offset:35584
	v_add_f32_dpp v28, v28, v28 row_ror:8 row_mask:0xf bank_mask:0x3
	v_add_f32_dpp v58, v58, v58 row_ror:8 row_mask:0xf bank_mask:0xc
	v_add_f32_dpp v22, v22, v22 quad_perm:[1,0,3,2] row_mask:0xf bank_mask:0xf
	v_add_f32_dpp v23, v23, v23 quad_perm:[1,0,3,2] row_mask:0xf bank_mask:0xf
	v_pk_fma_f32 v[84:85], v[48:49], v[56:57], v[84:85] op_sel:[0,0,0] op_sel_hi:[0,1,1]
	v_mov_b32_dpp v28, v58 quad_perm:[0,1,2,3] row_mask:0xf bank_mask:0xc
	v_add_f32_dpp v22, v22, v22 quad_perm:[2,3,0,1] row_mask:0xf bank_mask:0xf
	v_add_f32_dpp v23, v23, v23 quad_perm:[2,3,0,1] row_mask:0xf bank_mask:0xf
	v_pk_fma_f32 v[86:87], v[48:49], v[56:57], v[86:87] op_sel:[1,0,0] op_sel_hi:[1,1,1]
	v_add_f32_dpp v28, v28, v28 quad_perm:[1,0,3,2] row_mask:0xf bank_mask:0xf
	v_add_f32_dpp v22, v22, v22 row_half_mirror row_mask:0xf bank_mask:0xf
	v_add_f32_dpp v23, v23, v23 row_half_mirror row_mask:0xf bank_mask:0xf
	v_pk_fma_f32 v[88:89], v[50:51], v[56:57], v[88:89] op_sel:[0,0,0] op_sel_hi:[0,1,1]
	v_add_f32_dpp v28, v28, v28 quad_perm:[2,3,0,1] row_mask:0xf bank_mask:0xf
	v_add_f32_dpp v22, v22, v22 row_mirror row_mask:0xf bank_mask:0xf
	v_add_f32_dpp v23, v23, v23 row_mirror row_mask:0xf bank_mask:0xf
	v_pk_fma_f32 v[90:91], v[50:51], v[56:57], v[90:91] op_sel:[1,0,0] op_sel_hi:[1,1,1]
	v_cndmask_b32_e64 v30, v30, v28, s[10:11]
	v_pk_fma_f32 v[2:3], v[44:45], v[22:23], v[84:85] op_sel:[0,0,0] op_sel_hi:[0,1,1] neg_lo:[1,0,0] neg_hi:[1,0,0]
	v_pk_fma_f32 v[4:5], v[44:45], v[22:23], v[86:87] op_sel:[1,0,0] op_sel_hi:[1,1,1] neg_lo:[1,0,0] neg_hi:[1,0,0]
	v_pk_fma_f32 v[6:7], v[46:47], v[22:23], v[88:89] op_sel:[0,0,0] op_sel_hi:[0,1,1] neg_lo:[1,0,0] neg_hi:[1,0,0]
	v_pk_fma_f32 v[8:9], v[46:47], v[22:23], v[90:91] op_sel:[1,0,0] op_sel_hi:[1,1,1] neg_lo:[1,0,0] neg_hi:[1,0,0]
	s_waitcnt lgkmcnt(0)
	ds_read_b128 v[36:39], v20 offset:3072
	ds_read_b128 v[40:43], v20 offset:11264
	ds_read_b64 v[56:57], v21 offset:44032
	ds_read_b128 v[48:51], v20 offset:27648
	ds_read_b128 v[44:47], v20 offset:19456
	v_pk_mul_f32 v[22:23], v[2:3], v[60:61] op_sel:[0,0] op_sel_hi:[1,0]
	v_pk_mul_f32 v[28:29], v[2:3], v[52:53] op_sel:[0,0] op_sel_hi:[1,0]
	v_pk_mul_f32 v[84:85], v[2:3], v[64:65] op_sel:[0,0] op_sel_hi:[1,0]
	v_pk_fma_f32 v[22:23], v[4:5], v[60:61], v[22:23] op_sel:[0,1,0] op_sel_hi:[1,1,1]
	v_pk_fma_f32 v[28:29], v[4:5], v[52:53], v[28:29] op_sel:[0,1,0] op_sel_hi:[1,1,1]
	v_pk_mul_f32 v[86:87], v[4:5], v[64:65] op_sel:[0,1] op_sel_hi:[1,1]
	v_pk_fma_f32 v[22:23], v[6:7], v[62:63], v[22:23] op_sel:[0,0,0] op_sel_hi:[1,0,1]
	v_pk_fma_f32 v[28:29], v[6:7], v[54:55], v[28:29] op_sel:[0,0,0] op_sel_hi:[1,0,1]
	v_pk_mul_f32 v[88:89], v[6:7], v[66:67] op_sel:[0,0] op_sel_hi:[1,0]
	v_pk_fma_f32 v[22:23], v[8:9], v[62:63], v[22:23] op_sel:[0,1,0] op_sel_hi:[1,1,1]
	v_pk_fma_f32 v[28:29], v[8:9], v[54:55], v[28:29] op_sel:[0,1,0] op_sel_hi:[1,1,1]
	v_pk_mul_f32 v[90:91], v[8:9], v[66:67] op_sel:[0,1] op_sel_hi:[1,1]
	ds_read_b128 v[52:55], v20 offset:35840
	v_add_f32_dpp v24, v24, v24 row_ror:12 row_mask:0xf bank_mask:0x5
	v_add_f32_dpp v25, v25, v25 row_ror:4 row_mask:0xf bank_mask:0xa
	v_add_f32_dpp v22, v22, v22 quad_perm:[1,0,3,2] row_mask:0xf bank_mask:0xf
	v_add_f32_dpp v23, v23, v23 quad_perm:[1,0,3,2] row_mask:0xf bank_mask:0xf
	v_pk_fma_f32 v[84:85], v[72:73], v[80:81], v[84:85] op_sel:[0,0,0] op_sel_hi:[0,1,1]
	v_add_f32_dpp v26, v26, v26 row_ror:12 row_mask:0xf bank_mask:0x5
	v_add_f32_dpp v22, v22, v22 quad_perm:[2,3,0,1] row_mask:0xf bank_mask:0xf
	v_add_f32_dpp v23, v23, v23 quad_perm:[2,3,0,1] row_mask:0xf bank_mask:0xf
	v_pk_fma_f32 v[86:87], v[72:73], v[80:81], v[86:87] op_sel:[1,0,0] op_sel_hi:[1,1,1]
	v_add_f32_dpp v27, v27, v27 row_ror:4 row_mask:0xf bank_mask:0xa
	v_add_f32_dpp v22, v22, v22 row_half_mirror row_mask:0xf bank_mask:0xf
	v_add_f32_dpp v23, v23, v23 row_half_mirror row_mask:0xf bank_mask:0xf
	v_pk_fma_f32 v[88:89], v[74:75], v[80:81], v[88:89] op_sel:[0,0,0] op_sel_hi:[0,1,1]
	v_mov_b32_dpp v24, v25 quad_perm:[0,1,2,3] row_mask:0xf bank_mask:0xa
	v_add_f32_dpp v22, v22, v22 row_mirror row_mask:0xf bank_mask:0xf
	v_add_f32_dpp v23, v23, v23 row_mirror row_mask:0xf bank_mask:0xf
	v_pk_fma_f32 v[90:91], v[74:75], v[80:81], v[90:91] op_sel:[1,0,0] op_sel_hi:[1,1,1]
	v_mov_b32_dpp v26, v27 quad_perm:[0,1,2,3] row_mask:0xf bank_mask:0xa
	v_pk_fma_f32 v[2:3], v[68:69], v[22:23], v[84:85] op_sel:[0,0,0] op_sel_hi:[0,1,1] neg_lo:[1,0,0] neg_hi:[1,0,0]
	v_pk_fma_f32 v[4:5], v[68:69], v[22:23], v[86:87] op_sel:[1,0,0] op_sel_hi:[1,1,1] neg_lo:[1,0,0] neg_hi:[1,0,0]
	v_pk_fma_f32 v[6:7], v[70:71], v[22:23], v[88:89] op_sel:[0,0,0] op_sel_hi:[0,1,1] neg_lo:[1,0,0] neg_hi:[1,0,0]
	v_pk_fma_f32 v[8:9], v[70:71], v[22:23], v[90:91] op_sel:[1,0,0] op_sel_hi:[1,1,1] neg_lo:[1,0,0] neg_hi:[1,0,0]
	s_waitcnt lgkmcnt(0)
	ds_read_b128 v[60:63], v20 offset:3328
	ds_read_b128 v[64:67], v20 offset:11520
	ds_read_b64 v[80:81], v21 offset:44288
	ds_read_b128 v[72:75], v20 offset:27904
	ds_read_b128 v[68:71], v20 offset:19712
	v_pk_mul_f32 v[22:23], v[2:3], v[36:37] op_sel:[0,0] op_sel_hi:[1,0]
	v_pk_mul_f32 v[58:59], v[2:3], v[76:77] op_sel:[0,0] op_sel_hi:[1,0]
	v_pk_mul_f32 v[84:85], v[2:3], v[40:41] op_sel:[0,0] op_sel_hi:[1,0]
	v_pk_fma_f32 v[22:23], v[4:5], v[36:37], v[22:23] op_sel:[0,1,0] op_sel_hi:[1,1,1]
	v_pk_fma_f32 v[58:59], v[4:5], v[76:77], v[58:59] op_sel:[0,1,0] op_sel_hi:[1,1,1]
	v_pk_mul_f32 v[86:87], v[4:5], v[40:41] op_sel:[0,1] op_sel_hi:[1,1]
	v_pk_fma_f32 v[22:23], v[6:7], v[38:39], v[22:23] op_sel:[0,0,0] op_sel_hi:[1,0,1]
	v_pk_fma_f32 v[58:59], v[6:7], v[78:79], v[58:59] op_sel:[0,0,0] op_sel_hi:[1,0,1]
	v_pk_mul_f32 v[88:89], v[6:7], v[42:43] op_sel:[0,0] op_sel_hi:[1,0]
	v_pk_fma_f32 v[22:23], v[8:9], v[38:39], v[22:23] op_sel:[0,1,0] op_sel_hi:[1,1,1]
	v_pk_fma_f32 v[58:59], v[8:9], v[78:79], v[58:59] op_sel:[0,1,0] op_sel_hi:[1,1,1]
	v_pk_mul_f32 v[90:91], v[8:9], v[42:43] op_sel:[0,1] op_sel_hi:[1,1]
	ds_read_b128 v[76:79], v20 offset:36096
	v_add_f32_dpp v24, v24, v24 row_ror:8 row_mask:0xf bank_mask:0x3
	v_add_f32_dpp v26, v26, v26 row_ror:8 row_mask:0xf bank_mask:0xc
	v_add_f32_dpp v22, v22, v22 quad_perm:[1,0,3,2] row_mask:0xf bank_mask:0xf
	v_add_f32_dpp v23, v23, v23 quad_perm:[1,0,3,2] row_mask:0xf bank_mask:0xf
	v_pk_fma_f32 v[84:85], v[48:49], v[56:57], v[84:85] op_sel:[0,0,0] op_sel_hi:[0,1,1]
	v_mov_b32_dpp v24, v26 quad_perm:[0,1,2,3] row_mask:0xf bank_mask:0xc
	v_add_f32_dpp v22, v22, v22 quad_perm:[2,3,0,1] row_mask:0xf bank_mask:0xf
	v_add_f32_dpp v23, v23, v23 quad_perm:[2,3,0,1] row_mask:0xf bank_mask:0xf
	v_pk_fma_f32 v[86:87], v[48:49], v[56:57], v[86:87] op_sel:[1,0,0] op_sel_hi:[1,1,1]
	v_add_f32_dpp v24, v24, v24 quad_perm:[1,0,3,2] row_mask:0xf bank_mask:0xf
	v_add_f32_dpp v22, v22, v22 row_half_mirror row_mask:0xf bank_mask:0xf
	v_add_f32_dpp v23, v23, v23 row_half_mirror row_mask:0xf bank_mask:0xf
	v_pk_fma_f32 v[88:89], v[50:51], v[56:57], v[88:89] op_sel:[0,0,0] op_sel_hi:[0,1,1]
	v_add_f32_dpp v24, v24, v24 quad_perm:[2,3,0,1] row_mask:0xf bank_mask:0xf
	v_add_f32_dpp v22, v22, v22 row_mirror row_mask:0xf bank_mask:0xf
	v_add_f32_dpp v23, v23, v23 row_mirror row_mask:0xf bank_mask:0xf
	v_pk_fma_f32 v[90:91], v[50:51], v[56:57], v[90:91] op_sel:[1,0,0] op_sel_hi:[1,1,1]
	v_cndmask_b32_e64 v31, 0, v24, s[0:1]
	v_pk_fma_f32 v[2:3], v[44:45], v[22:23], v[84:85] op_sel:[0,0,0] op_sel_hi:[0,1,1] neg_lo:[1,0,0] neg_hi:[1,0,0]
	v_pk_fma_f32 v[4:5], v[44:45], v[22:23], v[86:87] op_sel:[1,0,0] op_sel_hi:[1,1,1] neg_lo:[1,0,0] neg_hi:[1,0,0]
	v_pk_fma_f32 v[6:7], v[46:47], v[22:23], v[88:89] op_sel:[0,0,0] op_sel_hi:[0,1,1] neg_lo:[1,0,0] neg_hi:[1,0,0]
	v_pk_fma_f32 v[8:9], v[46:47], v[22:23], v[90:91] op_sel:[1,0,0] op_sel_hi:[1,1,1] neg_lo:[1,0,0] neg_hi:[1,0,0]
	s_waitcnt lgkmcnt(0)
	ds_read_b128 v[36:39], v20 offset:3584
	ds_read_b128 v[40:43], v20 offset:11776
	ds_read_b64 v[56:57], v21 offset:44544
	ds_read_b128 v[48:51], v20 offset:28160
	ds_read_b128 v[44:47], v20 offset:19968
	v_pk_mul_f32 v[22:23], v[2:3], v[60:61] op_sel:[0,0] op_sel_hi:[1,0]
	v_pk_mul_f32 v[24:25], v[2:3], v[52:53] op_sel:[0,0] op_sel_hi:[1,0]
	v_pk_mul_f32 v[84:85], v[2:3], v[64:65] op_sel:[0,0] op_sel_hi:[1,0]
	v_pk_fma_f32 v[22:23], v[4:5], v[60:61], v[22:23] op_sel:[0,1,0] op_sel_hi:[1,1,1]
	v_pk_fma_f32 v[24:25], v[4:5], v[52:53], v[24:25] op_sel:[0,1,0] op_sel_hi:[1,1,1]
	v_pk_mul_f32 v[86:87], v[4:5], v[64:65] op_sel:[0,1] op_sel_hi:[1,1]
	v_pk_fma_f32 v[22:23], v[6:7], v[62:63], v[22:23] op_sel:[0,0,0] op_sel_hi:[1,0,1]
	v_pk_fma_f32 v[24:25], v[6:7], v[54:55], v[24:25] op_sel:[0,0,0] op_sel_hi:[1,0,1]
	v_pk_mul_f32 v[88:89], v[6:7], v[66:67] op_sel:[0,0] op_sel_hi:[1,0]
	v_pk_fma_f32 v[22:23], v[8:9], v[62:63], v[22:23] op_sel:[0,1,0] op_sel_hi:[1,1,1]
	v_pk_fma_f32 v[24:25], v[8:9], v[54:55], v[24:25] op_sel:[0,1,0] op_sel_hi:[1,1,1]
	v_pk_mul_f32 v[90:91], v[8:9], v[66:67] op_sel:[0,1] op_sel_hi:[1,1]
	ds_read_b128 v[52:55], v20 offset:36352
	v_add_f32_dpp v28, v28, v28 row_ror:12 row_mask:0xf bank_mask:0x5
	v_add_f32_dpp v29, v29, v29 row_ror:4 row_mask:0xf bank_mask:0xa
	v_add_f32_dpp v22, v22, v22 quad_perm:[1,0,3,2] row_mask:0xf bank_mask:0xf
	v_add_f32_dpp v23, v23, v23 quad_perm:[1,0,3,2] row_mask:0xf bank_mask:0xf
	v_pk_fma_f32 v[84:85], v[72:73], v[80:81], v[84:85] op_sel:[0,0,0] op_sel_hi:[0,1,1]
	v_add_f32_dpp v58, v58, v58 row_ror:12 row_mask:0xf bank_mask:0x5
	v_add_f32_dpp v22, v22, v22 quad_perm:[2,3,0,1] row_mask:0xf bank_mask:0xf
	v_add_f32_dpp v23, v23, v23 quad_perm:[2,3,0,1] row_mask:0xf bank_mask:0xf
	v_pk_fma_f32 v[86:87], v[72:73], v[80:81], v[86:87] op_sel:[1,0,0] op_sel_hi:[1,1,1]
	v_add_f32_dpp v59, v59, v59 row_ror:4 row_mask:0xf bank_mask:0xa
	v_add_f32_dpp v22, v22, v22 row_half_mirror row_mask:0xf bank_mask:0xf
	v_add_f32_dpp v23, v23, v23 row_half_mirror row_mask:0xf bank_mask:0xf
	v_pk_fma_f32 v[88:89], v[74:75], v[80:81], v[88:89] op_sel:[0,0,0] op_sel_hi:[0,1,1]
	v_mov_b32_dpp v28, v29 quad_perm:[0,1,2,3] row_mask:0xf bank_mask:0xa
	v_add_f32_dpp v22, v22, v22 row_mirror row_mask:0xf bank_mask:0xf
	v_add_f32_dpp v23, v23, v23 row_mirror row_mask:0xf bank_mask:0xf
	v_pk_fma_f32 v[90:91], v[74:75], v[80:81], v[90:91] op_sel:[1,0,0] op_sel_hi:[1,1,1]
	v_mov_b32_dpp v58, v59 quad_perm:[0,1,2,3] row_mask:0xf bank_mask:0xa
	v_pk_fma_f32 v[2:3], v[68:69], v[22:23], v[84:85] op_sel:[0,0,0] op_sel_hi:[0,1,1] neg_lo:[1,0,0] neg_hi:[1,0,0]
	v_pk_fma_f32 v[4:5], v[68:69], v[22:23], v[86:87] op_sel:[1,0,0] op_sel_hi:[1,1,1] neg_lo:[1,0,0] neg_hi:[1,0,0]
	v_pk_fma_f32 v[6:7], v[70:71], v[22:23], v[88:89] op_sel:[0,0,0] op_sel_hi:[0,1,1] neg_lo:[1,0,0] neg_hi:[1,0,0]
	v_pk_fma_f32 v[8:9], v[70:71], v[22:23], v[90:91] op_sel:[1,0,0] op_sel_hi:[1,1,1] neg_lo:[1,0,0] neg_hi:[1,0,0]
	s_waitcnt lgkmcnt(0)
	ds_read_b128 v[60:63], v20 offset:3840
	ds_read_b128 v[64:67], v20 offset:12032
	ds_read_b64 v[80:81], v21 offset:44800
	ds_read_b128 v[72:75], v20 offset:28416
	ds_read_b128 v[68:71], v20 offset:20224
	v_pk_mul_f32 v[22:23], v[2:3], v[36:37] op_sel:[0,0] op_sel_hi:[1,0]
	v_pk_mul_f32 v[26:27], v[2:3], v[76:77] op_sel:[0,0] op_sel_hi:[1,0]
	v_pk_mul_f32 v[84:85], v[2:3], v[40:41] op_sel:[0,0] op_sel_hi:[1,0]
	v_pk_fma_f32 v[22:23], v[4:5], v[36:37], v[22:23] op_sel:[0,1,0] op_sel_hi:[1,1,1]
	v_pk_fma_f32 v[26:27], v[4:5], v[76:77], v[26:27] op_sel:[0,1,0] op_sel_hi:[1,1,1]
	v_pk_mul_f32 v[86:87], v[4:5], v[40:41] op_sel:[0,1] op_sel_hi:[1,1]
	v_pk_fma_f32 v[22:23], v[6:7], v[38:39], v[22:23] op_sel:[0,0,0] op_sel_hi:[1,0,1]
	v_pk_fma_f32 v[26:27], v[6:7], v[78:79], v[26:27] op_sel:[0,0,0] op_sel_hi:[1,0,1]
	v_pk_mul_f32 v[88:89], v[6:7], v[42:43] op_sel:[0,0] op_sel_hi:[1,0]
	v_pk_fma_f32 v[22:23], v[8:9], v[38:39], v[22:23] op_sel:[0,1,0] op_sel_hi:[1,1,1]
	v_pk_fma_f32 v[26:27], v[8:9], v[78:79], v[26:27] op_sel:[0,1,0] op_sel_hi:[1,1,1]
	v_pk_mul_f32 v[90:91], v[8:9], v[42:43] op_sel:[0,1] op_sel_hi:[1,1]
	ds_read_b128 v[76:79], v20 offset:36608
	v_add_f32_dpp v28, v28, v28 row_ror:8 row_mask:0xf bank_mask:0x3
	v_add_f32_dpp v58, v58, v58 row_ror:8 row_mask:0xf bank_mask:0xc
	v_add_f32_dpp v22, v22, v22 quad_perm:[1,0,3,2] row_mask:0xf bank_mask:0xf
	v_add_f32_dpp v23, v23, v23 quad_perm:[1,0,3,2] row_mask:0xf bank_mask:0xf
	v_pk_fma_f32 v[84:85], v[48:49], v[56:57], v[84:85] op_sel:[0,0,0] op_sel_hi:[0,1,1]
	v_mov_b32_dpp v28, v58 quad_perm:[0,1,2,3] row_mask:0xf bank_mask:0xc
	v_add_f32_dpp v22, v22, v22 quad_perm:[2,3,0,1] row_mask:0xf bank_mask:0xf
	v_add_f32_dpp v23, v23, v23 quad_perm:[2,3,0,1] row_mask:0xf bank_mask:0xf
	v_pk_fma_f32 v[86:87], v[48:49], v[56:57], v[86:87] op_sel:[1,0,0] op_sel_hi:[1,1,1]
	v_add_f32_dpp v28, v28, v28 quad_perm:[1,0,3,2] row_mask:0xf bank_mask:0xf
	v_add_f32_dpp v22, v22, v22 row_half_mirror row_mask:0xf bank_mask:0xf
	v_add_f32_dpp v23, v23, v23 row_half_mirror row_mask:0xf bank_mask:0xf
	v_pk_fma_f32 v[88:89], v[50:51], v[56:57], v[88:89] op_sel:[0,0,0] op_sel_hi:[0,1,1]
	v_add_f32_dpp v28, v28, v28 quad_perm:[2,3,0,1] row_mask:0xf bank_mask:0xf
	v_add_f32_dpp v22, v22, v22 row_mirror row_mask:0xf bank_mask:0xf
	v_add_f32_dpp v23, v23, v23 row_mirror row_mask:0xf bank_mask:0xf
	v_pk_fma_f32 v[90:91], v[50:51], v[56:57], v[90:91] op_sel:[1,0,0] op_sel_hi:[1,1,1]
	v_cndmask_b32_e64 v31, v31, v28, s[6:7]
	v_pk_fma_f32 v[2:3], v[44:45], v[22:23], v[84:85] op_sel:[0,0,0] op_sel_hi:[0,1,1] neg_lo:[1,0,0] neg_hi:[1,0,0]
	v_pk_fma_f32 v[4:5], v[44:45], v[22:23], v[86:87] op_sel:[1,0,0] op_sel_hi:[1,1,1] neg_lo:[1,0,0] neg_hi:[1,0,0]
	v_pk_fma_f32 v[6:7], v[46:47], v[22:23], v[88:89] op_sel:[0,0,0] op_sel_hi:[0,1,1] neg_lo:[1,0,0] neg_hi:[1,0,0]
	v_pk_fma_f32 v[8:9], v[46:47], v[22:23], v[90:91] op_sel:[1,0,0] op_sel_hi:[1,1,1] neg_lo:[1,0,0] neg_hi:[1,0,0]
	s_waitcnt lgkmcnt(0)
	ds_read_b128 v[36:39], v20 offset:4096
	ds_read_b128 v[40:43], v20 offset:12288
	ds_read_b64 v[56:57], v21 offset:45056
	ds_read_b128 v[48:51], v20 offset:28672
	ds_read_b128 v[44:47], v20 offset:20480
	v_pk_mul_f32 v[22:23], v[2:3], v[60:61] op_sel:[0,0] op_sel_hi:[1,0]
	v_pk_mul_f32 v[28:29], v[2:3], v[52:53] op_sel:[0,0] op_sel_hi:[1,0]
	v_pk_mul_f32 v[84:85], v[2:3], v[64:65] op_sel:[0,0] op_sel_hi:[1,0]
	v_pk_fma_f32 v[22:23], v[4:5], v[60:61], v[22:23] op_sel:[0,1,0] op_sel_hi:[1,1,1]
	v_pk_fma_f32 v[28:29], v[4:5], v[52:53], v[28:29] op_sel:[0,1,0] op_sel_hi:[1,1,1]
	v_pk_mul_f32 v[86:87], v[4:5], v[64:65] op_sel:[0,1] op_sel_hi:[1,1]
	v_pk_fma_f32 v[22:23], v[6:7], v[62:63], v[22:23] op_sel:[0,0,0] op_sel_hi:[1,0,1]
	v_pk_fma_f32 v[28:29], v[6:7], v[54:55], v[28:29] op_sel:[0,0,0] op_sel_hi:[1,0,1]
	v_pk_mul_f32 v[88:89], v[6:7], v[66:67] op_sel:[0,0] op_sel_hi:[1,0]
	v_pk_fma_f32 v[22:23], v[8:9], v[62:63], v[22:23] op_sel:[0,1,0] op_sel_hi:[1,1,1]
	v_pk_fma_f32 v[28:29], v[8:9], v[54:55], v[28:29] op_sel:[0,1,0] op_sel_hi:[1,1,1]
	v_pk_mul_f32 v[90:91], v[8:9], v[66:67] op_sel:[0,1] op_sel_hi:[1,1]
	ds_read_b128 v[52:55], v20 offset:36864
	v_add_f32_dpp v24, v24, v24 row_ror:12 row_mask:0xf bank_mask:0x5
	v_add_f32_dpp v25, v25, v25 row_ror:4 row_mask:0xf bank_mask:0xa
	v_add_f32_dpp v22, v22, v22 quad_perm:[1,0,3,2] row_mask:0xf bank_mask:0xf
	v_add_f32_dpp v23, v23, v23 quad_perm:[1,0,3,2] row_mask:0xf bank_mask:0xf
	v_pk_fma_f32 v[84:85], v[72:73], v[80:81], v[84:85] op_sel:[0,0,0] op_sel_hi:[0,1,1]
	v_add_f32_dpp v26, v26, v26 row_ror:12 row_mask:0xf bank_mask:0x5
	v_add_f32_dpp v22, v22, v22 quad_perm:[2,3,0,1] row_mask:0xf bank_mask:0xf
	v_add_f32_dpp v23, v23, v23 quad_perm:[2,3,0,1] row_mask:0xf bank_mask:0xf
	v_pk_fma_f32 v[86:87], v[72:73], v[80:81], v[86:87] op_sel:[1,0,0] op_sel_hi:[1,1,1]
	v_add_f32_dpp v27, v27, v27 row_ror:4 row_mask:0xf bank_mask:0xa
	v_add_f32_dpp v22, v22, v22 row_half_mirror row_mask:0xf bank_mask:0xf
	v_add_f32_dpp v23, v23, v23 row_half_mirror row_mask:0xf bank_mask:0xf
	v_pk_fma_f32 v[88:89], v[74:75], v[80:81], v[88:89] op_sel:[0,0,0] op_sel_hi:[0,1,1]
	v_mov_b32_dpp v24, v25 quad_perm:[0,1,2,3] row_mask:0xf bank_mask:0xa
	v_add_f32_dpp v22, v22, v22 row_mirror row_mask:0xf bank_mask:0xf
	v_add_f32_dpp v23, v23, v23 row_mirror row_mask:0xf bank_mask:0xf
	v_pk_fma_f32 v[90:91], v[74:75], v[80:81], v[90:91] op_sel:[1,0,0] op_sel_hi:[1,1,1]
	v_mov_b32_dpp v26, v27 quad_perm:[0,1,2,3] row_mask:0xf bank_mask:0xa
	v_pk_fma_f32 v[2:3], v[68:69], v[22:23], v[84:85] op_sel:[0,0,0] op_sel_hi:[0,1,1] neg_lo:[1,0,0] neg_hi:[1,0,0]
	v_pk_fma_f32 v[4:5], v[68:69], v[22:23], v[86:87] op_sel:[1,0,0] op_sel_hi:[1,1,1] neg_lo:[1,0,0] neg_hi:[1,0,0]
	v_pk_fma_f32 v[6:7], v[70:71], v[22:23], v[88:89] op_sel:[0,0,0] op_sel_hi:[0,1,1] neg_lo:[1,0,0] neg_hi:[1,0,0]
	v_pk_fma_f32 v[8:9], v[70:71], v[22:23], v[90:91] op_sel:[1,0,0] op_sel_hi:[1,1,1] neg_lo:[1,0,0] neg_hi:[1,0,0]
	s_waitcnt lgkmcnt(0)
	ds_read_b128 v[60:63], v20 offset:4352
	ds_read_b128 v[64:67], v20 offset:12544
	ds_read_b64 v[80:81], v21 offset:45312
	ds_read_b128 v[72:75], v20 offset:28928
	ds_read_b128 v[68:71], v20 offset:20736
	v_pk_mul_f32 v[22:23], v[2:3], v[36:37] op_sel:[0,0] op_sel_hi:[1,0]
	v_pk_mul_f32 v[58:59], v[2:3], v[76:77] op_sel:[0,0] op_sel_hi:[1,0]
	v_pk_mul_f32 v[84:85], v[2:3], v[40:41] op_sel:[0,0] op_sel_hi:[1,0]
	v_pk_fma_f32 v[22:23], v[4:5], v[36:37], v[22:23] op_sel:[0,1,0] op_sel_hi:[1,1,1]
	v_pk_fma_f32 v[58:59], v[4:5], v[76:77], v[58:59] op_sel:[0,1,0] op_sel_hi:[1,1,1]
	v_pk_mul_f32 v[86:87], v[4:5], v[40:41] op_sel:[0,1] op_sel_hi:[1,1]
	v_pk_fma_f32 v[22:23], v[6:7], v[38:39], v[22:23] op_sel:[0,0,0] op_sel_hi:[1,0,1]
	v_pk_fma_f32 v[58:59], v[6:7], v[78:79], v[58:59] op_sel:[0,0,0] op_sel_hi:[1,0,1]
	v_pk_mul_f32 v[88:89], v[6:7], v[42:43] op_sel:[0,0] op_sel_hi:[1,0]
	v_pk_fma_f32 v[22:23], v[8:9], v[38:39], v[22:23] op_sel:[0,1,0] op_sel_hi:[1,1,1]
	v_pk_fma_f32 v[58:59], v[8:9], v[78:79], v[58:59] op_sel:[0,1,0] op_sel_hi:[1,1,1]
	v_pk_mul_f32 v[90:91], v[8:9], v[42:43] op_sel:[0,1] op_sel_hi:[1,1]
	ds_read_b128 v[76:79], v20 offset:37120
	v_add_f32_dpp v24, v24, v24 row_ror:8 row_mask:0xf bank_mask:0x3
	v_add_f32_dpp v26, v26, v26 row_ror:8 row_mask:0xf bank_mask:0xc
	v_add_f32_dpp v22, v22, v22 quad_perm:[1,0,3,2] row_mask:0xf bank_mask:0xf
	v_add_f32_dpp v23, v23, v23 quad_perm:[1,0,3,2] row_mask:0xf bank_mask:0xf
	v_pk_fma_f32 v[84:85], v[48:49], v[56:57], v[84:85] op_sel:[0,0,0] op_sel_hi:[0,1,1]
	v_mov_b32_dpp v24, v26 quad_perm:[0,1,2,3] row_mask:0xf bank_mask:0xc
	v_add_f32_dpp v22, v22, v22 quad_perm:[2,3,0,1] row_mask:0xf bank_mask:0xf
	v_add_f32_dpp v23, v23, v23 quad_perm:[2,3,0,1] row_mask:0xf bank_mask:0xf
	v_pk_fma_f32 v[86:87], v[48:49], v[56:57], v[86:87] op_sel:[1,0,0] op_sel_hi:[1,1,1]
	v_add_f32_dpp v24, v24, v24 quad_perm:[1,0,3,2] row_mask:0xf bank_mask:0xf
	v_add_f32_dpp v22, v22, v22 row_half_mirror row_mask:0xf bank_mask:0xf
	v_add_f32_dpp v23, v23, v23 row_half_mirror row_mask:0xf bank_mask:0xf
	v_pk_fma_f32 v[88:89], v[50:51], v[56:57], v[88:89] op_sel:[0,0,0] op_sel_hi:[0,1,1]
	v_add_f32_dpp v24, v24, v24 quad_perm:[2,3,0,1] row_mask:0xf bank_mask:0xf
	v_add_f32_dpp v22, v22, v22 row_mirror row_mask:0xf bank_mask:0xf
	v_add_f32_dpp v23, v23, v23 row_mirror row_mask:0xf bank_mask:0xf
	v_pk_fma_f32 v[90:91], v[50:51], v[56:57], v[90:91] op_sel:[1,0,0] op_sel_hi:[1,1,1]
	v_cndmask_b32_e64 v31, v31, v24, s[8:9]
	v_pk_fma_f32 v[2:3], v[44:45], v[22:23], v[84:85] op_sel:[0,0,0] op_sel_hi:[0,1,1] neg_lo:[1,0,0] neg_hi:[1,0,0]
	v_pk_fma_f32 v[4:5], v[44:45], v[22:23], v[86:87] op_sel:[1,0,0] op_sel_hi:[1,1,1] neg_lo:[1,0,0] neg_hi:[1,0,0]
	v_pk_fma_f32 v[6:7], v[46:47], v[22:23], v[88:89] op_sel:[0,0,0] op_sel_hi:[0,1,1] neg_lo:[1,0,0] neg_hi:[1,0,0]
	v_pk_fma_f32 v[8:9], v[46:47], v[22:23], v[90:91] op_sel:[1,0,0] op_sel_hi:[1,1,1] neg_lo:[1,0,0] neg_hi:[1,0,0]
	s_waitcnt lgkmcnt(0)
	ds_read_b128 v[36:39], v20 offset:4608
	ds_read_b128 v[40:43], v20 offset:12800
	ds_read_b64 v[56:57], v21 offset:45568
	ds_read_b128 v[48:51], v20 offset:29184
	ds_read_b128 v[44:47], v20 offset:20992
	v_pk_mul_f32 v[22:23], v[2:3], v[60:61] op_sel:[0,0] op_sel_hi:[1,0]
	v_pk_mul_f32 v[24:25], v[2:3], v[52:53] op_sel:[0,0] op_sel_hi:[1,0]
	v_pk_mul_f32 v[84:85], v[2:3], v[64:65] op_sel:[0,0] op_sel_hi:[1,0]
	v_pk_fma_f32 v[22:23], v[4:5], v[60:61], v[22:23] op_sel:[0,1,0] op_sel_hi:[1,1,1]
	v_pk_fma_f32 v[24:25], v[4:5], v[52:53], v[24:25] op_sel:[0,1,0] op_sel_hi:[1,1,1]
	v_pk_mul_f32 v[86:87], v[4:5], v[64:65] op_sel:[0,1] op_sel_hi:[1,1]
	v_pk_fma_f32 v[22:23], v[6:7], v[62:63], v[22:23] op_sel:[0,0,0] op_sel_hi:[1,0,1]
	v_pk_fma_f32 v[24:25], v[6:7], v[54:55], v[24:25] op_sel:[0,0,0] op_sel_hi:[1,0,1]
	v_pk_mul_f32 v[88:89], v[6:7], v[66:67] op_sel:[0,0] op_sel_hi:[1,0]
	v_pk_fma_f32 v[22:23], v[8:9], v[62:63], v[22:23] op_sel:[0,1,0] op_sel_hi:[1,1,1]
	v_pk_fma_f32 v[24:25], v[8:9], v[54:55], v[24:25] op_sel:[0,1,0] op_sel_hi:[1,1,1]
	v_pk_mul_f32 v[90:91], v[8:9], v[66:67] op_sel:[0,1] op_sel_hi:[1,1]
	ds_read_b128 v[52:55], v20 offset:37376
	v_add_f32_dpp v28, v28, v28 row_ror:12 row_mask:0xf bank_mask:0x5
	v_add_f32_dpp v29, v29, v29 row_ror:4 row_mask:0xf bank_mask:0xa
	v_add_f32_dpp v22, v22, v22 quad_perm:[1,0,3,2] row_mask:0xf bank_mask:0xf
	v_add_f32_dpp v23, v23, v23 quad_perm:[1,0,3,2] row_mask:0xf bank_mask:0xf
	v_pk_fma_f32 v[84:85], v[72:73], v[80:81], v[84:85] op_sel:[0,0,0] op_sel_hi:[0,1,1]
	v_add_f32_dpp v58, v58, v58 row_ror:12 row_mask:0xf bank_mask:0x5
	v_add_f32_dpp v22, v22, v22 quad_perm:[2,3,0,1] row_mask:0xf bank_mask:0xf
	v_add_f32_dpp v23, v23, v23 quad_perm:[2,3,0,1] row_mask:0xf bank_mask:0xf
	v_pk_fma_f32 v[86:87], v[72:73], v[80:81], v[86:87] op_sel:[1,0,0] op_sel_hi:[1,1,1]
	v_add_f32_dpp v59, v59, v59 row_ror:4 row_mask:0xf bank_mask:0xa
	v_add_f32_dpp v22, v22, v22 row_half_mirror row_mask:0xf bank_mask:0xf
	v_add_f32_dpp v23, v23, v23 row_half_mirror row_mask:0xf bank_mask:0xf
	v_pk_fma_f32 v[88:89], v[74:75], v[80:81], v[88:89] op_sel:[0,0,0] op_sel_hi:[0,1,1]
	v_mov_b32_dpp v28, v29 quad_perm:[0,1,2,3] row_mask:0xf bank_mask:0xa
	v_add_f32_dpp v22, v22, v22 row_mirror row_mask:0xf bank_mask:0xf
	v_add_f32_dpp v23, v23, v23 row_mirror row_mask:0xf bank_mask:0xf
	v_pk_fma_f32 v[90:91], v[74:75], v[80:81], v[90:91] op_sel:[1,0,0] op_sel_hi:[1,1,1]
	v_mov_b32_dpp v58, v59 quad_perm:[0,1,2,3] row_mask:0xf bank_mask:0xa
	v_pk_fma_f32 v[2:3], v[68:69], v[22:23], v[84:85] op_sel:[0,0,0] op_sel_hi:[0,1,1] neg_lo:[1,0,0] neg_hi:[1,0,0]
	v_pk_fma_f32 v[4:5], v[68:69], v[22:23], v[86:87] op_sel:[1,0,0] op_sel_hi:[1,1,1] neg_lo:[1,0,0] neg_hi:[1,0,0]
	v_pk_fma_f32 v[6:7], v[70:71], v[22:23], v[88:89] op_sel:[0,0,0] op_sel_hi:[0,1,1] neg_lo:[1,0,0] neg_hi:[1,0,0]
	v_pk_fma_f32 v[8:9], v[70:71], v[22:23], v[90:91] op_sel:[1,0,0] op_sel_hi:[1,1,1] neg_lo:[1,0,0] neg_hi:[1,0,0]
	s_waitcnt lgkmcnt(0)
	ds_read_b128 v[60:63], v20 offset:4864
	ds_read_b128 v[64:67], v20 offset:13056
	ds_read_b64 v[80:81], v21 offset:45824
	ds_read_b128 v[72:75], v20 offset:29440
	ds_read_b128 v[68:71], v20 offset:21248
	v_pk_mul_f32 v[22:23], v[2:3], v[36:37] op_sel:[0,0] op_sel_hi:[1,0]
	v_pk_mul_f32 v[26:27], v[2:3], v[76:77] op_sel:[0,0] op_sel_hi:[1,0]
	v_pk_mul_f32 v[84:85], v[2:3], v[40:41] op_sel:[0,0] op_sel_hi:[1,0]
	v_pk_fma_f32 v[22:23], v[4:5], v[36:37], v[22:23] op_sel:[0,1,0] op_sel_hi:[1,1,1]
	v_pk_fma_f32 v[26:27], v[4:5], v[76:77], v[26:27] op_sel:[0,1,0] op_sel_hi:[1,1,1]
	v_pk_mul_f32 v[86:87], v[4:5], v[40:41] op_sel:[0,1] op_sel_hi:[1,1]
	v_pk_fma_f32 v[22:23], v[6:7], v[38:39], v[22:23] op_sel:[0,0,0] op_sel_hi:[1,0,1]
	v_pk_fma_f32 v[26:27], v[6:7], v[78:79], v[26:27] op_sel:[0,0,0] op_sel_hi:[1,0,1]
	v_pk_mul_f32 v[88:89], v[6:7], v[42:43] op_sel:[0,0] op_sel_hi:[1,0]
	v_pk_fma_f32 v[22:23], v[8:9], v[38:39], v[22:23] op_sel:[0,1,0] op_sel_hi:[1,1,1]
	v_pk_fma_f32 v[26:27], v[8:9], v[78:79], v[26:27] op_sel:[0,1,0] op_sel_hi:[1,1,1]
	v_pk_mul_f32 v[90:91], v[8:9], v[42:43] op_sel:[0,1] op_sel_hi:[1,1]
	ds_read_b128 v[76:79], v20 offset:37632
	v_add_f32_dpp v28, v28, v28 row_ror:8 row_mask:0xf bank_mask:0x3
	v_add_f32_dpp v58, v58, v58 row_ror:8 row_mask:0xf bank_mask:0xc
	v_add_f32_dpp v22, v22, v22 quad_perm:[1,0,3,2] row_mask:0xf bank_mask:0xf
	v_add_f32_dpp v23, v23, v23 quad_perm:[1,0,3,2] row_mask:0xf bank_mask:0xf
	v_pk_fma_f32 v[84:85], v[48:49], v[56:57], v[84:85] op_sel:[0,0,0] op_sel_hi:[0,1,1]
	v_mov_b32_dpp v28, v58 quad_perm:[0,1,2,3] row_mask:0xf bank_mask:0xc
	v_add_f32_dpp v22, v22, v22 quad_perm:[2,3,0,1] row_mask:0xf bank_mask:0xf
	v_add_f32_dpp v23, v23, v23 quad_perm:[2,3,0,1] row_mask:0xf bank_mask:0xf
	v_pk_fma_f32 v[86:87], v[48:49], v[56:57], v[86:87] op_sel:[1,0,0] op_sel_hi:[1,1,1]
	v_add_f32_dpp v28, v28, v28 quad_perm:[1,0,3,2] row_mask:0xf bank_mask:0xf
	v_add_f32_dpp v22, v22, v22 row_half_mirror row_mask:0xf bank_mask:0xf
	v_add_f32_dpp v23, v23, v23 row_half_mirror row_mask:0xf bank_mask:0xf
	v_pk_fma_f32 v[88:89], v[50:51], v[56:57], v[88:89] op_sel:[0,0,0] op_sel_hi:[0,1,1]
	v_add_f32_dpp v28, v28, v28 quad_perm:[2,3,0,1] row_mask:0xf bank_mask:0xf
	v_add_f32_dpp v22, v22, v22 row_mirror row_mask:0xf bank_mask:0xf
	v_add_f32_dpp v23, v23, v23 row_mirror row_mask:0xf bank_mask:0xf
	v_pk_fma_f32 v[90:91], v[50:51], v[56:57], v[90:91] op_sel:[1,0,0] op_sel_hi:[1,1,1]
	v_cndmask_b32_e64 v31, v31, v28, s[10:11]
	v_pk_fma_f32 v[2:3], v[44:45], v[22:23], v[84:85] op_sel:[0,0,0] op_sel_hi:[0,1,1] neg_lo:[1,0,0] neg_hi:[1,0,0]
	v_pk_fma_f32 v[4:5], v[44:45], v[22:23], v[86:87] op_sel:[1,0,0] op_sel_hi:[1,1,1] neg_lo:[1,0,0] neg_hi:[1,0,0]
	v_pk_fma_f32 v[6:7], v[46:47], v[22:23], v[88:89] op_sel:[0,0,0] op_sel_hi:[0,1,1] neg_lo:[1,0,0] neg_hi:[1,0,0]
	v_pk_fma_f32 v[8:9], v[46:47], v[22:23], v[90:91] op_sel:[1,0,0] op_sel_hi:[1,1,1] neg_lo:[1,0,0] neg_hi:[1,0,0]
	s_waitcnt lgkmcnt(0)
	ds_read_b128 v[36:39], v20 offset:5120
	ds_read_b128 v[40:43], v20 offset:13312
	ds_read_b64 v[56:57], v21 offset:46080
	ds_read_b128 v[48:51], v20 offset:29696
	ds_read_b128 v[44:47], v20 offset:21504
	v_pk_mul_f32 v[22:23], v[2:3], v[60:61] op_sel:[0,0] op_sel_hi:[1,0]
	v_pk_mul_f32 v[28:29], v[2:3], v[52:53] op_sel:[0,0] op_sel_hi:[1,0]
	v_pk_mul_f32 v[84:85], v[2:3], v[64:65] op_sel:[0,0] op_sel_hi:[1,0]
	v_pk_fma_f32 v[22:23], v[4:5], v[60:61], v[22:23] op_sel:[0,1,0] op_sel_hi:[1,1,1]
	v_pk_fma_f32 v[28:29], v[4:5], v[52:53], v[28:29] op_sel:[0,1,0] op_sel_hi:[1,1,1]
	v_pk_mul_f32 v[86:87], v[4:5], v[64:65] op_sel:[0,1] op_sel_hi:[1,1]
	v_pk_fma_f32 v[22:23], v[6:7], v[62:63], v[22:23] op_sel:[0,0,0] op_sel_hi:[1,0,1]
	v_pk_fma_f32 v[28:29], v[6:7], v[54:55], v[28:29] op_sel:[0,0,0] op_sel_hi:[1,0,1]
	v_pk_mul_f32 v[88:89], v[6:7], v[66:67] op_sel:[0,0] op_sel_hi:[1,0]
	v_pk_fma_f32 v[22:23], v[8:9], v[62:63], v[22:23] op_sel:[0,1,0] op_sel_hi:[1,1,1]
	v_pk_fma_f32 v[28:29], v[8:9], v[54:55], v[28:29] op_sel:[0,1,0] op_sel_hi:[1,1,1]
	v_pk_mul_f32 v[90:91], v[8:9], v[66:67] op_sel:[0,1] op_sel_hi:[1,1]
	ds_read_b128 v[52:55], v20 offset:37888
	v_add_f32_dpp v24, v24, v24 row_ror:12 row_mask:0xf bank_mask:0x5
	v_add_f32_dpp v25, v25, v25 row_ror:4 row_mask:0xf bank_mask:0xa
	v_add_f32_dpp v22, v22, v22 quad_perm:[1,0,3,2] row_mask:0xf bank_mask:0xf
	v_add_f32_dpp v23, v23, v23 quad_perm:[1,0,3,2] row_mask:0xf bank_mask:0xf
	v_pk_fma_f32 v[84:85], v[72:73], v[80:81], v[84:85] op_sel:[0,0,0] op_sel_hi:[0,1,1]
	v_add_f32_dpp v26, v26, v26 row_ror:12 row_mask:0xf bank_mask:0x5
	v_add_f32_dpp v22, v22, v22 quad_perm:[2,3,0,1] row_mask:0xf bank_mask:0xf
	v_add_f32_dpp v23, v23, v23 quad_perm:[2,3,0,1] row_mask:0xf bank_mask:0xf
	v_pk_fma_f32 v[86:87], v[72:73], v[80:81], v[86:87] op_sel:[1,0,0] op_sel_hi:[1,1,1]
	v_add_f32_dpp v27, v27, v27 row_ror:4 row_mask:0xf bank_mask:0xa
	v_add_f32_dpp v22, v22, v22 row_half_mirror row_mask:0xf bank_mask:0xf
	v_add_f32_dpp v23, v23, v23 row_half_mirror row_mask:0xf bank_mask:0xf
	v_pk_fma_f32 v[88:89], v[74:75], v[80:81], v[88:89] op_sel:[0,0,0] op_sel_hi:[0,1,1]
	v_mov_b32_dpp v24, v25 quad_perm:[0,1,2,3] row_mask:0xf bank_mask:0xa
	v_add_f32_dpp v22, v22, v22 row_mirror row_mask:0xf bank_mask:0xf
	v_add_f32_dpp v23, v23, v23 row_mirror row_mask:0xf bank_mask:0xf
	v_pk_fma_f32 v[90:91], v[74:75], v[80:81], v[90:91] op_sel:[1,0,0] op_sel_hi:[1,1,1]
	v_mov_b32_dpp v26, v27 quad_perm:[0,1,2,3] row_mask:0xf bank_mask:0xa
	v_pk_fma_f32 v[2:3], v[68:69], v[22:23], v[84:85] op_sel:[0,0,0] op_sel_hi:[0,1,1] neg_lo:[1,0,0] neg_hi:[1,0,0]
	v_pk_fma_f32 v[4:5], v[68:69], v[22:23], v[86:87] op_sel:[1,0,0] op_sel_hi:[1,1,1] neg_lo:[1,0,0] neg_hi:[1,0,0]
	v_pk_fma_f32 v[6:7], v[70:71], v[22:23], v[88:89] op_sel:[0,0,0] op_sel_hi:[0,1,1] neg_lo:[1,0,0] neg_hi:[1,0,0]
	v_pk_fma_f32 v[8:9], v[70:71], v[22:23], v[90:91] op_sel:[1,0,0] op_sel_hi:[1,1,1] neg_lo:[1,0,0] neg_hi:[1,0,0]
	s_waitcnt lgkmcnt(0)
	ds_read_b128 v[60:63], v20 offset:5376
	ds_read_b128 v[64:67], v20 offset:13568
	ds_read_b64 v[80:81], v21 offset:46336
	ds_read_b128 v[72:75], v20 offset:29952
	ds_read_b128 v[68:71], v20 offset:21760
	v_pk_mul_f32 v[22:23], v[2:3], v[36:37] op_sel:[0,0] op_sel_hi:[1,0]
	v_pk_mul_f32 v[58:59], v[2:3], v[76:77] op_sel:[0,0] op_sel_hi:[1,0]
	v_pk_mul_f32 v[84:85], v[2:3], v[40:41] op_sel:[0,0] op_sel_hi:[1,0]
	v_pk_fma_f32 v[22:23], v[4:5], v[36:37], v[22:23] op_sel:[0,1,0] op_sel_hi:[1,1,1]
	v_pk_fma_f32 v[58:59], v[4:5], v[76:77], v[58:59] op_sel:[0,1,0] op_sel_hi:[1,1,1]
	v_pk_mul_f32 v[86:87], v[4:5], v[40:41] op_sel:[0,1] op_sel_hi:[1,1]
	v_pk_fma_f32 v[22:23], v[6:7], v[38:39], v[22:23] op_sel:[0,0,0] op_sel_hi:[1,0,1]
	v_pk_fma_f32 v[58:59], v[6:7], v[78:79], v[58:59] op_sel:[0,0,0] op_sel_hi:[1,0,1]
	v_pk_mul_f32 v[88:89], v[6:7], v[42:43] op_sel:[0,0] op_sel_hi:[1,0]
	v_pk_fma_f32 v[22:23], v[8:9], v[38:39], v[22:23] op_sel:[0,1,0] op_sel_hi:[1,1,1]
	v_pk_fma_f32 v[58:59], v[8:9], v[78:79], v[58:59] op_sel:[0,1,0] op_sel_hi:[1,1,1]
	v_pk_mul_f32 v[90:91], v[8:9], v[42:43] op_sel:[0,1] op_sel_hi:[1,1]
	ds_read_b128 v[76:79], v20 offset:38144
	v_add_f32_dpp v24, v24, v24 row_ror:8 row_mask:0xf bank_mask:0x3
	v_add_f32_dpp v26, v26, v26 row_ror:8 row_mask:0xf bank_mask:0xc
	v_add_f32_dpp v22, v22, v22 quad_perm:[1,0,3,2] row_mask:0xf bank_mask:0xf
	v_add_f32_dpp v23, v23, v23 quad_perm:[1,0,3,2] row_mask:0xf bank_mask:0xf
	v_pk_fma_f32 v[84:85], v[48:49], v[56:57], v[84:85] op_sel:[0,0,0] op_sel_hi:[0,1,1]
	v_mov_b32_dpp v24, v26 quad_perm:[0,1,2,3] row_mask:0xf bank_mask:0xc
	v_add_f32_dpp v22, v22, v22 quad_perm:[2,3,0,1] row_mask:0xf bank_mask:0xf
	v_add_f32_dpp v23, v23, v23 quad_perm:[2,3,0,1] row_mask:0xf bank_mask:0xf
	v_pk_fma_f32 v[86:87], v[48:49], v[56:57], v[86:87] op_sel:[1,0,0] op_sel_hi:[1,1,1]
	v_add_f32_dpp v24, v24, v24 quad_perm:[1,0,3,2] row_mask:0xf bank_mask:0xf
	v_add_f32_dpp v22, v22, v22 row_half_mirror row_mask:0xf bank_mask:0xf
	v_add_f32_dpp v23, v23, v23 row_half_mirror row_mask:0xf bank_mask:0xf
	v_pk_fma_f32 v[88:89], v[50:51], v[56:57], v[88:89] op_sel:[0,0,0] op_sel_hi:[0,1,1]
	v_add_f32_dpp v24, v24, v24 quad_perm:[2,3,0,1] row_mask:0xf bank_mask:0xf
	v_add_f32_dpp v22, v22, v22 row_mirror row_mask:0xf bank_mask:0xf
	v_add_f32_dpp v23, v23, v23 row_mirror row_mask:0xf bank_mask:0xf
	v_pk_fma_f32 v[90:91], v[50:51], v[56:57], v[90:91] op_sel:[1,0,0] op_sel_hi:[1,1,1]
	v_cndmask_b32_e64 v32, 0, v24, s[0:1]
	v_pk_fma_f32 v[2:3], v[44:45], v[22:23], v[84:85] op_sel:[0,0,0] op_sel_hi:[0,1,1] neg_lo:[1,0,0] neg_hi:[1,0,0]
	v_pk_fma_f32 v[4:5], v[44:45], v[22:23], v[86:87] op_sel:[1,0,0] op_sel_hi:[1,1,1] neg_lo:[1,0,0] neg_hi:[1,0,0]
	v_pk_fma_f32 v[6:7], v[46:47], v[22:23], v[88:89] op_sel:[0,0,0] op_sel_hi:[0,1,1] neg_lo:[1,0,0] neg_hi:[1,0,0]
	v_pk_fma_f32 v[8:9], v[46:47], v[22:23], v[90:91] op_sel:[1,0,0] op_sel_hi:[1,1,1] neg_lo:[1,0,0] neg_hi:[1,0,0]
	s_waitcnt lgkmcnt(0)
	ds_read_b128 v[36:39], v20 offset:5632
	ds_read_b128 v[40:43], v20 offset:13824
	ds_read_b64 v[56:57], v21 offset:46592
	ds_read_b128 v[48:51], v20 offset:30208
	ds_read_b128 v[44:47], v20 offset:22016
	v_pk_mul_f32 v[22:23], v[2:3], v[60:61] op_sel:[0,0] op_sel_hi:[1,0]
	v_pk_mul_f32 v[24:25], v[2:3], v[52:53] op_sel:[0,0] op_sel_hi:[1,0]
	v_pk_mul_f32 v[84:85], v[2:3], v[64:65] op_sel:[0,0] op_sel_hi:[1,0]
	v_pk_fma_f32 v[22:23], v[4:5], v[60:61], v[22:23] op_sel:[0,1,0] op_sel_hi:[1,1,1]
	v_pk_fma_f32 v[24:25], v[4:5], v[52:53], v[24:25] op_sel:[0,1,0] op_sel_hi:[1,1,1]
	v_pk_mul_f32 v[86:87], v[4:5], v[64:65] op_sel:[0,1] op_sel_hi:[1,1]
	v_pk_fma_f32 v[22:23], v[6:7], v[62:63], v[22:23] op_sel:[0,0,0] op_sel_hi:[1,0,1]
	v_pk_fma_f32 v[24:25], v[6:7], v[54:55], v[24:25] op_sel:[0,0,0] op_sel_hi:[1,0,1]
	v_pk_mul_f32 v[88:89], v[6:7], v[66:67] op_sel:[0,0] op_sel_hi:[1,0]
	v_pk_fma_f32 v[22:23], v[8:9], v[62:63], v[22:23] op_sel:[0,1,0] op_sel_hi:[1,1,1]
	v_pk_fma_f32 v[24:25], v[8:9], v[54:55], v[24:25] op_sel:[0,1,0] op_sel_hi:[1,1,1]
	v_pk_mul_f32 v[90:91], v[8:9], v[66:67] op_sel:[0,1] op_sel_hi:[1,1]
	ds_read_b128 v[52:55], v20 offset:38400
	v_add_f32_dpp v28, v28, v28 row_ror:12 row_mask:0xf bank_mask:0x5
	v_add_f32_dpp v29, v29, v29 row_ror:4 row_mask:0xf bank_mask:0xa
	v_add_f32_dpp v22, v22, v22 quad_perm:[1,0,3,2] row_mask:0xf bank_mask:0xf
	v_add_f32_dpp v23, v23, v23 quad_perm:[1,0,3,2] row_mask:0xf bank_mask:0xf
	v_pk_fma_f32 v[84:85], v[72:73], v[80:81], v[84:85] op_sel:[0,0,0] op_sel_hi:[0,1,1]
	v_add_f32_dpp v58, v58, v58 row_ror:12 row_mask:0xf bank_mask:0x5
	v_add_f32_dpp v22, v22, v22 quad_perm:[2,3,0,1] row_mask:0xf bank_mask:0xf
	v_add_f32_dpp v23, v23, v23 quad_perm:[2,3,0,1] row_mask:0xf bank_mask:0xf
	v_pk_fma_f32 v[86:87], v[72:73], v[80:81], v[86:87] op_sel:[1,0,0] op_sel_hi:[1,1,1]
	v_add_f32_dpp v59, v59, v59 row_ror:4 row_mask:0xf bank_mask:0xa
	v_add_f32_dpp v22, v22, v22 row_half_mirror row_mask:0xf bank_mask:0xf
	v_add_f32_dpp v23, v23, v23 row_half_mirror row_mask:0xf bank_mask:0xf
	v_pk_fma_f32 v[88:89], v[74:75], v[80:81], v[88:89] op_sel:[0,0,0] op_sel_hi:[0,1,1]
	v_mov_b32_dpp v28, v29 quad_perm:[0,1,2,3] row_mask:0xf bank_mask:0xa
	v_add_f32_dpp v22, v22, v22 row_mirror row_mask:0xf bank_mask:0xf
	v_add_f32_dpp v23, v23, v23 row_mirror row_mask:0xf bank_mask:0xf
	v_pk_fma_f32 v[90:91], v[74:75], v[80:81], v[90:91] op_sel:[1,0,0] op_sel_hi:[1,1,1]
	v_mov_b32_dpp v58, v59 quad_perm:[0,1,2,3] row_mask:0xf bank_mask:0xa
	v_pk_fma_f32 v[2:3], v[68:69], v[22:23], v[84:85] op_sel:[0,0,0] op_sel_hi:[0,1,1] neg_lo:[1,0,0] neg_hi:[1,0,0]
	v_pk_fma_f32 v[4:5], v[68:69], v[22:23], v[86:87] op_sel:[1,0,0] op_sel_hi:[1,1,1] neg_lo:[1,0,0] neg_hi:[1,0,0]
	v_pk_fma_f32 v[6:7], v[70:71], v[22:23], v[88:89] op_sel:[0,0,0] op_sel_hi:[0,1,1] neg_lo:[1,0,0] neg_hi:[1,0,0]
	v_pk_fma_f32 v[8:9], v[70:71], v[22:23], v[90:91] op_sel:[1,0,0] op_sel_hi:[1,1,1] neg_lo:[1,0,0] neg_hi:[1,0,0]
	s_waitcnt lgkmcnt(0)
	ds_read_b128 v[60:63], v20 offset:5888
	ds_read_b128 v[64:67], v20 offset:14080
	ds_read_b64 v[80:81], v21 offset:46848
	ds_read_b128 v[72:75], v20 offset:30464
	ds_read_b128 v[68:71], v20 offset:22272
	v_pk_mul_f32 v[22:23], v[2:3], v[36:37] op_sel:[0,0] op_sel_hi:[1,0]
	v_pk_mul_f32 v[26:27], v[2:3], v[76:77] op_sel:[0,0] op_sel_hi:[1,0]
	v_pk_mul_f32 v[84:85], v[2:3], v[40:41] op_sel:[0,0] op_sel_hi:[1,0]
	v_pk_fma_f32 v[22:23], v[4:5], v[36:37], v[22:23] op_sel:[0,1,0] op_sel_hi:[1,1,1]
	v_pk_fma_f32 v[26:27], v[4:5], v[76:77], v[26:27] op_sel:[0,1,0] op_sel_hi:[1,1,1]
	v_pk_mul_f32 v[86:87], v[4:5], v[40:41] op_sel:[0,1] op_sel_hi:[1,1]
	v_pk_fma_f32 v[22:23], v[6:7], v[38:39], v[22:23] op_sel:[0,0,0] op_sel_hi:[1,0,1]
	v_pk_fma_f32 v[26:27], v[6:7], v[78:79], v[26:27] op_sel:[0,0,0] op_sel_hi:[1,0,1]
	v_pk_mul_f32 v[88:89], v[6:7], v[42:43] op_sel:[0,0] op_sel_hi:[1,0]
	v_pk_fma_f32 v[22:23], v[8:9], v[38:39], v[22:23] op_sel:[0,1,0] op_sel_hi:[1,1,1]
	v_pk_fma_f32 v[26:27], v[8:9], v[78:79], v[26:27] op_sel:[0,1,0] op_sel_hi:[1,1,1]
	v_pk_mul_f32 v[90:91], v[8:9], v[42:43] op_sel:[0,1] op_sel_hi:[1,1]
	ds_read_b128 v[76:79], v20 offset:38656
	v_add_f32_dpp v28, v28, v28 row_ror:8 row_mask:0xf bank_mask:0x3
	v_add_f32_dpp v58, v58, v58 row_ror:8 row_mask:0xf bank_mask:0xc
	v_add_f32_dpp v22, v22, v22 quad_perm:[1,0,3,2] row_mask:0xf bank_mask:0xf
	v_add_f32_dpp v23, v23, v23 quad_perm:[1,0,3,2] row_mask:0xf bank_mask:0xf
	v_pk_fma_f32 v[84:85], v[48:49], v[56:57], v[84:85] op_sel:[0,0,0] op_sel_hi:[0,1,1]
	v_mov_b32_dpp v28, v58 quad_perm:[0,1,2,3] row_mask:0xf bank_mask:0xc
	v_add_f32_dpp v22, v22, v22 quad_perm:[2,3,0,1] row_mask:0xf bank_mask:0xf
	v_add_f32_dpp v23, v23, v23 quad_perm:[2,3,0,1] row_mask:0xf bank_mask:0xf
	v_pk_fma_f32 v[86:87], v[48:49], v[56:57], v[86:87] op_sel:[1,0,0] op_sel_hi:[1,1,1]
	v_add_f32_dpp v28, v28, v28 quad_perm:[1,0,3,2] row_mask:0xf bank_mask:0xf
	v_add_f32_dpp v22, v22, v22 row_half_mirror row_mask:0xf bank_mask:0xf
	v_add_f32_dpp v23, v23, v23 row_half_mirror row_mask:0xf bank_mask:0xf
	v_pk_fma_f32 v[88:89], v[50:51], v[56:57], v[88:89] op_sel:[0,0,0] op_sel_hi:[0,1,1]
	v_add_f32_dpp v28, v28, v28 quad_perm:[2,3,0,1] row_mask:0xf bank_mask:0xf
	v_add_f32_dpp v22, v22, v22 row_mirror row_mask:0xf bank_mask:0xf
	v_add_f32_dpp v23, v23, v23 row_mirror row_mask:0xf bank_mask:0xf
	v_pk_fma_f32 v[90:91], v[50:51], v[56:57], v[90:91] op_sel:[1,0,0] op_sel_hi:[1,1,1]
	v_cndmask_b32_e64 v32, v32, v28, s[6:7]
	v_pk_fma_f32 v[2:3], v[44:45], v[22:23], v[84:85] op_sel:[0,0,0] op_sel_hi:[0,1,1] neg_lo:[1,0,0] neg_hi:[1,0,0]
	v_pk_fma_f32 v[4:5], v[44:45], v[22:23], v[86:87] op_sel:[1,0,0] op_sel_hi:[1,1,1] neg_lo:[1,0,0] neg_hi:[1,0,0]
	v_pk_fma_f32 v[6:7], v[46:47], v[22:23], v[88:89] op_sel:[0,0,0] op_sel_hi:[0,1,1] neg_lo:[1,0,0] neg_hi:[1,0,0]
	v_pk_fma_f32 v[8:9], v[46:47], v[22:23], v[90:91] op_sel:[1,0,0] op_sel_hi:[1,1,1] neg_lo:[1,0,0] neg_hi:[1,0,0]
	s_waitcnt lgkmcnt(0)
	ds_read_b128 v[36:39], v20 offset:6144
	ds_read_b128 v[40:43], v20 offset:14336
	ds_read_b64 v[56:57], v21 offset:47104
	ds_read_b128 v[48:51], v20 offset:30720
	ds_read_b128 v[44:47], v20 offset:22528
	v_pk_mul_f32 v[22:23], v[2:3], v[60:61] op_sel:[0,0] op_sel_hi:[1,0]
	v_pk_mul_f32 v[28:29], v[2:3], v[52:53] op_sel:[0,0] op_sel_hi:[1,0]
	v_pk_mul_f32 v[84:85], v[2:3], v[64:65] op_sel:[0,0] op_sel_hi:[1,0]
	v_pk_fma_f32 v[22:23], v[4:5], v[60:61], v[22:23] op_sel:[0,1,0] op_sel_hi:[1,1,1]
	v_pk_fma_f32 v[28:29], v[4:5], v[52:53], v[28:29] op_sel:[0,1,0] op_sel_hi:[1,1,1]
	v_pk_mul_f32 v[86:87], v[4:5], v[64:65] op_sel:[0,1] op_sel_hi:[1,1]
	v_pk_fma_f32 v[22:23], v[6:7], v[62:63], v[22:23] op_sel:[0,0,0] op_sel_hi:[1,0,1]
	v_pk_fma_f32 v[28:29], v[6:7], v[54:55], v[28:29] op_sel:[0,0,0] op_sel_hi:[1,0,1]
	v_pk_mul_f32 v[88:89], v[6:7], v[66:67] op_sel:[0,0] op_sel_hi:[1,0]
	v_pk_fma_f32 v[22:23], v[8:9], v[62:63], v[22:23] op_sel:[0,1,0] op_sel_hi:[1,1,1]
	v_pk_fma_f32 v[28:29], v[8:9], v[54:55], v[28:29] op_sel:[0,1,0] op_sel_hi:[1,1,1]
	v_pk_mul_f32 v[90:91], v[8:9], v[66:67] op_sel:[0,1] op_sel_hi:[1,1]
	ds_read_b128 v[52:55], v20 offset:38912
	v_add_f32_dpp v24, v24, v24 row_ror:12 row_mask:0xf bank_mask:0x5
	v_add_f32_dpp v25, v25, v25 row_ror:4 row_mask:0xf bank_mask:0xa
	v_add_f32_dpp v22, v22, v22 quad_perm:[1,0,3,2] row_mask:0xf bank_mask:0xf
	v_add_f32_dpp v23, v23, v23 quad_perm:[1,0,3,2] row_mask:0xf bank_mask:0xf
	v_pk_fma_f32 v[84:85], v[72:73], v[80:81], v[84:85] op_sel:[0,0,0] op_sel_hi:[0,1,1]
	v_add_f32_dpp v26, v26, v26 row_ror:12 row_mask:0xf bank_mask:0x5
	v_add_f32_dpp v22, v22, v22 quad_perm:[2,3,0,1] row_mask:0xf bank_mask:0xf
	v_add_f32_dpp v23, v23, v23 quad_perm:[2,3,0,1] row_mask:0xf bank_mask:0xf
	v_pk_fma_f32 v[86:87], v[72:73], v[80:81], v[86:87] op_sel:[1,0,0] op_sel_hi:[1,1,1]
	v_add_f32_dpp v27, v27, v27 row_ror:4 row_mask:0xf bank_mask:0xa
	v_add_f32_dpp v22, v22, v22 row_half_mirror row_mask:0xf bank_mask:0xf
	v_add_f32_dpp v23, v23, v23 row_half_mirror row_mask:0xf bank_mask:0xf
	v_pk_fma_f32 v[88:89], v[74:75], v[80:81], v[88:89] op_sel:[0,0,0] op_sel_hi:[0,1,1]
	v_mov_b32_dpp v24, v25 quad_perm:[0,1,2,3] row_mask:0xf bank_mask:0xa
	v_add_f32_dpp v22, v22, v22 row_mirror row_mask:0xf bank_mask:0xf
	v_add_f32_dpp v23, v23, v23 row_mirror row_mask:0xf bank_mask:0xf
	v_pk_fma_f32 v[90:91], v[74:75], v[80:81], v[90:91] op_sel:[1,0,0] op_sel_hi:[1,1,1]
	v_mov_b32_dpp v26, v27 quad_perm:[0,1,2,3] row_mask:0xf bank_mask:0xa
	v_pk_fma_f32 v[2:3], v[68:69], v[22:23], v[84:85] op_sel:[0,0,0] op_sel_hi:[0,1,1] neg_lo:[1,0,0] neg_hi:[1,0,0]
	v_pk_fma_f32 v[4:5], v[68:69], v[22:23], v[86:87] op_sel:[1,0,0] op_sel_hi:[1,1,1] neg_lo:[1,0,0] neg_hi:[1,0,0]
	v_pk_fma_f32 v[6:7], v[70:71], v[22:23], v[88:89] op_sel:[0,0,0] op_sel_hi:[0,1,1] neg_lo:[1,0,0] neg_hi:[1,0,0]
	v_pk_fma_f32 v[8:9], v[70:71], v[22:23], v[90:91] op_sel:[1,0,0] op_sel_hi:[1,1,1] neg_lo:[1,0,0] neg_hi:[1,0,0]
	s_waitcnt lgkmcnt(0)
	ds_read_b128 v[60:63], v20 offset:6400
	ds_read_b128 v[64:67], v20 offset:14592
	ds_read_b64 v[80:81], v21 offset:47360
	ds_read_b128 v[72:75], v20 offset:30976
	ds_read_b128 v[68:71], v20 offset:22784
	v_pk_mul_f32 v[22:23], v[2:3], v[36:37] op_sel:[0,0] op_sel_hi:[1,0]
	v_pk_mul_f32 v[58:59], v[2:3], v[76:77] op_sel:[0,0] op_sel_hi:[1,0]
	v_pk_mul_f32 v[84:85], v[2:3], v[40:41] op_sel:[0,0] op_sel_hi:[1,0]
	v_pk_fma_f32 v[22:23], v[4:5], v[36:37], v[22:23] op_sel:[0,1,0] op_sel_hi:[1,1,1]
	v_pk_fma_f32 v[58:59], v[4:5], v[76:77], v[58:59] op_sel:[0,1,0] op_sel_hi:[1,1,1]
	v_pk_mul_f32 v[86:87], v[4:5], v[40:41] op_sel:[0,1] op_sel_hi:[1,1]
	v_pk_fma_f32 v[22:23], v[6:7], v[38:39], v[22:23] op_sel:[0,0,0] op_sel_hi:[1,0,1]
	v_pk_fma_f32 v[58:59], v[6:7], v[78:79], v[58:59] op_sel:[0,0,0] op_sel_hi:[1,0,1]
	v_pk_mul_f32 v[88:89], v[6:7], v[42:43] op_sel:[0,0] op_sel_hi:[1,0]
	v_pk_fma_f32 v[22:23], v[8:9], v[38:39], v[22:23] op_sel:[0,1,0] op_sel_hi:[1,1,1]
	v_pk_fma_f32 v[58:59], v[8:9], v[78:79], v[58:59] op_sel:[0,1,0] op_sel_hi:[1,1,1]
	v_pk_mul_f32 v[90:91], v[8:9], v[42:43] op_sel:[0,1] op_sel_hi:[1,1]
	ds_read_b128 v[76:79], v20 offset:39168
	v_add_f32_dpp v24, v24, v24 row_ror:8 row_mask:0xf bank_mask:0x3
	v_add_f32_dpp v26, v26, v26 row_ror:8 row_mask:0xf bank_mask:0xc
	v_add_f32_dpp v22, v22, v22 quad_perm:[1,0,3,2] row_mask:0xf bank_mask:0xf
	v_add_f32_dpp v23, v23, v23 quad_perm:[1,0,3,2] row_mask:0xf bank_mask:0xf
	v_pk_fma_f32 v[84:85], v[48:49], v[56:57], v[84:85] op_sel:[0,0,0] op_sel_hi:[0,1,1]
	v_mov_b32_dpp v24, v26 quad_perm:[0,1,2,3] row_mask:0xf bank_mask:0xc
	v_add_f32_dpp v22, v22, v22 quad_perm:[2,3,0,1] row_mask:0xf bank_mask:0xf
	v_add_f32_dpp v23, v23, v23 quad_perm:[2,3,0,1] row_mask:0xf bank_mask:0xf
	v_pk_fma_f32 v[86:87], v[48:49], v[56:57], v[86:87] op_sel:[1,0,0] op_sel_hi:[1,1,1]
	v_add_f32_dpp v24, v24, v24 quad_perm:[1,0,3,2] row_mask:0xf bank_mask:0xf
	v_add_f32_dpp v22, v22, v22 row_half_mirror row_mask:0xf bank_mask:0xf
	v_add_f32_dpp v23, v23, v23 row_half_mirror row_mask:0xf bank_mask:0xf
	v_pk_fma_f32 v[88:89], v[50:51], v[56:57], v[88:89] op_sel:[0,0,0] op_sel_hi:[0,1,1]
	v_add_f32_dpp v24, v24, v24 quad_perm:[2,3,0,1] row_mask:0xf bank_mask:0xf
	v_add_f32_dpp v22, v22, v22 row_mirror row_mask:0xf bank_mask:0xf
	v_add_f32_dpp v23, v23, v23 row_mirror row_mask:0xf bank_mask:0xf
	v_pk_fma_f32 v[90:91], v[50:51], v[56:57], v[90:91] op_sel:[1,0,0] op_sel_hi:[1,1,1]
	v_cndmask_b32_e64 v32, v32, v24, s[8:9]
	v_pk_fma_f32 v[2:3], v[44:45], v[22:23], v[84:85] op_sel:[0,0,0] op_sel_hi:[0,1,1] neg_lo:[1,0,0] neg_hi:[1,0,0]
	v_pk_fma_f32 v[4:5], v[44:45], v[22:23], v[86:87] op_sel:[1,0,0] op_sel_hi:[1,1,1] neg_lo:[1,0,0] neg_hi:[1,0,0]
	v_pk_fma_f32 v[6:7], v[46:47], v[22:23], v[88:89] op_sel:[0,0,0] op_sel_hi:[0,1,1] neg_lo:[1,0,0] neg_hi:[1,0,0]
	v_pk_fma_f32 v[8:9], v[46:47], v[22:23], v[90:91] op_sel:[1,0,0] op_sel_hi:[1,1,1] neg_lo:[1,0,0] neg_hi:[1,0,0]
	s_waitcnt lgkmcnt(0)
	ds_read_b128 v[36:39], v20 offset:6656
	ds_read_b128 v[40:43], v20 offset:14848
	ds_read_b64 v[56:57], v21 offset:47616
	ds_read_b128 v[48:51], v20 offset:31232
	ds_read_b128 v[44:47], v20 offset:23040
	v_pk_mul_f32 v[22:23], v[2:3], v[60:61] op_sel:[0,0] op_sel_hi:[1,0]
	v_pk_mul_f32 v[24:25], v[2:3], v[52:53] op_sel:[0,0] op_sel_hi:[1,0]
	v_pk_mul_f32 v[84:85], v[2:3], v[64:65] op_sel:[0,0] op_sel_hi:[1,0]
	v_pk_fma_f32 v[22:23], v[4:5], v[60:61], v[22:23] op_sel:[0,1,0] op_sel_hi:[1,1,1]
	v_pk_fma_f32 v[24:25], v[4:5], v[52:53], v[24:25] op_sel:[0,1,0] op_sel_hi:[1,1,1]
	v_pk_mul_f32 v[86:87], v[4:5], v[64:65] op_sel:[0,1] op_sel_hi:[1,1]
	v_pk_fma_f32 v[22:23], v[6:7], v[62:63], v[22:23] op_sel:[0,0,0] op_sel_hi:[1,0,1]
	v_pk_fma_f32 v[24:25], v[6:7], v[54:55], v[24:25] op_sel:[0,0,0] op_sel_hi:[1,0,1]
	v_pk_mul_f32 v[88:89], v[6:7], v[66:67] op_sel:[0,0] op_sel_hi:[1,0]
	v_pk_fma_f32 v[22:23], v[8:9], v[62:63], v[22:23] op_sel:[0,1,0] op_sel_hi:[1,1,1]
	v_pk_fma_f32 v[24:25], v[8:9], v[54:55], v[24:25] op_sel:[0,1,0] op_sel_hi:[1,1,1]
	v_pk_mul_f32 v[90:91], v[8:9], v[66:67] op_sel:[0,1] op_sel_hi:[1,1]
	ds_read_b128 v[52:55], v20 offset:39424
	v_add_f32_dpp v28, v28, v28 row_ror:12 row_mask:0xf bank_mask:0x5
	v_add_f32_dpp v29, v29, v29 row_ror:4 row_mask:0xf bank_mask:0xa
	v_add_f32_dpp v22, v22, v22 quad_perm:[1,0,3,2] row_mask:0xf bank_mask:0xf
	v_add_f32_dpp v23, v23, v23 quad_perm:[1,0,3,2] row_mask:0xf bank_mask:0xf
	v_pk_fma_f32 v[84:85], v[72:73], v[80:81], v[84:85] op_sel:[0,0,0] op_sel_hi:[0,1,1]
	v_add_f32_dpp v58, v58, v58 row_ror:12 row_mask:0xf bank_mask:0x5
	v_add_f32_dpp v22, v22, v22 quad_perm:[2,3,0,1] row_mask:0xf bank_mask:0xf
	v_add_f32_dpp v23, v23, v23 quad_perm:[2,3,0,1] row_mask:0xf bank_mask:0xf
	v_pk_fma_f32 v[86:87], v[72:73], v[80:81], v[86:87] op_sel:[1,0,0] op_sel_hi:[1,1,1]
	v_add_f32_dpp v59, v59, v59 row_ror:4 row_mask:0xf bank_mask:0xa
	v_add_f32_dpp v22, v22, v22 row_half_mirror row_mask:0xf bank_mask:0xf
	v_add_f32_dpp v23, v23, v23 row_half_mirror row_mask:0xf bank_mask:0xf
	v_pk_fma_f32 v[88:89], v[74:75], v[80:81], v[88:89] op_sel:[0,0,0] op_sel_hi:[0,1,1]
	v_mov_b32_dpp v28, v29 quad_perm:[0,1,2,3] row_mask:0xf bank_mask:0xa
	v_add_f32_dpp v22, v22, v22 row_mirror row_mask:0xf bank_mask:0xf
	v_add_f32_dpp v23, v23, v23 row_mirror row_mask:0xf bank_mask:0xf
	v_pk_fma_f32 v[90:91], v[74:75], v[80:81], v[90:91] op_sel:[1,0,0] op_sel_hi:[1,1,1]
	v_mov_b32_dpp v58, v59 quad_perm:[0,1,2,3] row_mask:0xf bank_mask:0xa
	v_pk_fma_f32 v[2:3], v[68:69], v[22:23], v[84:85] op_sel:[0,0,0] op_sel_hi:[0,1,1] neg_lo:[1,0,0] neg_hi:[1,0,0]
	v_pk_fma_f32 v[4:5], v[68:69], v[22:23], v[86:87] op_sel:[1,0,0] op_sel_hi:[1,1,1] neg_lo:[1,0,0] neg_hi:[1,0,0]
	v_pk_fma_f32 v[6:7], v[70:71], v[22:23], v[88:89] op_sel:[0,0,0] op_sel_hi:[0,1,1] neg_lo:[1,0,0] neg_hi:[1,0,0]
	v_pk_fma_f32 v[8:9], v[70:71], v[22:23], v[90:91] op_sel:[1,0,0] op_sel_hi:[1,1,1] neg_lo:[1,0,0] neg_hi:[1,0,0]
	s_waitcnt lgkmcnt(0)
	ds_read_b128 v[60:63], v20 offset:6912
	ds_read_b128 v[64:67], v20 offset:15104
	ds_read_b64 v[80:81], v21 offset:47872
	ds_read_b128 v[72:75], v20 offset:31488
	ds_read_b128 v[68:71], v20 offset:23296
	v_pk_mul_f32 v[22:23], v[2:3], v[36:37] op_sel:[0,0] op_sel_hi:[1,0]
	v_pk_mul_f32 v[26:27], v[2:3], v[76:77] op_sel:[0,0] op_sel_hi:[1,0]
	v_pk_mul_f32 v[84:85], v[2:3], v[40:41] op_sel:[0,0] op_sel_hi:[1,0]
	v_pk_fma_f32 v[22:23], v[4:5], v[36:37], v[22:23] op_sel:[0,1,0] op_sel_hi:[1,1,1]
	v_pk_fma_f32 v[26:27], v[4:5], v[76:77], v[26:27] op_sel:[0,1,0] op_sel_hi:[1,1,1]
	v_pk_mul_f32 v[86:87], v[4:5], v[40:41] op_sel:[0,1] op_sel_hi:[1,1]
	v_pk_fma_f32 v[22:23], v[6:7], v[38:39], v[22:23] op_sel:[0,0,0] op_sel_hi:[1,0,1]
	v_pk_fma_f32 v[26:27], v[6:7], v[78:79], v[26:27] op_sel:[0,0,0] op_sel_hi:[1,0,1]
	v_pk_mul_f32 v[88:89], v[6:7], v[42:43] op_sel:[0,0] op_sel_hi:[1,0]
	v_pk_fma_f32 v[22:23], v[8:9], v[38:39], v[22:23] op_sel:[0,1,0] op_sel_hi:[1,1,1]
	v_pk_fma_f32 v[26:27], v[8:9], v[78:79], v[26:27] op_sel:[0,1,0] op_sel_hi:[1,1,1]
	v_pk_mul_f32 v[90:91], v[8:9], v[42:43] op_sel:[0,1] op_sel_hi:[1,1]
	ds_read_b128 v[76:79], v20 offset:39680
	v_add_f32_dpp v28, v28, v28 row_ror:8 row_mask:0xf bank_mask:0x3
	v_add_f32_dpp v58, v58, v58 row_ror:8 row_mask:0xf bank_mask:0xc
	v_add_f32_dpp v22, v22, v22 quad_perm:[1,0,3,2] row_mask:0xf bank_mask:0xf
	v_add_f32_dpp v23, v23, v23 quad_perm:[1,0,3,2] row_mask:0xf bank_mask:0xf
	v_pk_fma_f32 v[84:85], v[48:49], v[56:57], v[84:85] op_sel:[0,0,0] op_sel_hi:[0,1,1]
	v_mov_b32_dpp v28, v58 quad_perm:[0,1,2,3] row_mask:0xf bank_mask:0xc
	v_add_f32_dpp v22, v22, v22 quad_perm:[2,3,0,1] row_mask:0xf bank_mask:0xf
	v_add_f32_dpp v23, v23, v23 quad_perm:[2,3,0,1] row_mask:0xf bank_mask:0xf
	v_pk_fma_f32 v[86:87], v[48:49], v[56:57], v[86:87] op_sel:[1,0,0] op_sel_hi:[1,1,1]
	v_add_f32_dpp v28, v28, v28 quad_perm:[1,0,3,2] row_mask:0xf bank_mask:0xf
	v_add_f32_dpp v22, v22, v22 row_half_mirror row_mask:0xf bank_mask:0xf
	v_add_f32_dpp v23, v23, v23 row_half_mirror row_mask:0xf bank_mask:0xf
	v_pk_fma_f32 v[88:89], v[50:51], v[56:57], v[88:89] op_sel:[0,0,0] op_sel_hi:[0,1,1]
	v_add_f32_dpp v28, v28, v28 quad_perm:[2,3,0,1] row_mask:0xf bank_mask:0xf
	v_add_f32_dpp v22, v22, v22 row_mirror row_mask:0xf bank_mask:0xf
	v_add_f32_dpp v23, v23, v23 row_mirror row_mask:0xf bank_mask:0xf
	v_pk_fma_f32 v[90:91], v[50:51], v[56:57], v[90:91] op_sel:[1,0,0] op_sel_hi:[1,1,1]
	v_cndmask_b32_e64 v32, v32, v28, s[10:11]
	v_pk_fma_f32 v[2:3], v[44:45], v[22:23], v[84:85] op_sel:[0,0,0] op_sel_hi:[0,1,1] neg_lo:[1,0,0] neg_hi:[1,0,0]
	v_pk_fma_f32 v[4:5], v[44:45], v[22:23], v[86:87] op_sel:[1,0,0] op_sel_hi:[1,1,1] neg_lo:[1,0,0] neg_hi:[1,0,0]
	v_pk_fma_f32 v[6:7], v[46:47], v[22:23], v[88:89] op_sel:[0,0,0] op_sel_hi:[0,1,1] neg_lo:[1,0,0] neg_hi:[1,0,0]
	v_pk_fma_f32 v[8:9], v[46:47], v[22:23], v[90:91] op_sel:[1,0,0] op_sel_hi:[1,1,1] neg_lo:[1,0,0] neg_hi:[1,0,0]
	s_waitcnt lgkmcnt(0)
	ds_read_b128 v[36:39], v20 offset:7168
	ds_read_b128 v[40:43], v20 offset:15360
	ds_read_b64 v[56:57], v21 offset:48128
	ds_read_b128 v[48:51], v20 offset:31744
	ds_read_b128 v[44:47], v20 offset:23552
	v_pk_mul_f32 v[22:23], v[2:3], v[60:61] op_sel:[0,0] op_sel_hi:[1,0]
	v_pk_mul_f32 v[28:29], v[2:3], v[52:53] op_sel:[0,0] op_sel_hi:[1,0]
	v_pk_mul_f32 v[84:85], v[2:3], v[64:65] op_sel:[0,0] op_sel_hi:[1,0]
	v_pk_fma_f32 v[22:23], v[4:5], v[60:61], v[22:23] op_sel:[0,1,0] op_sel_hi:[1,1,1]
	v_pk_fma_f32 v[28:29], v[4:5], v[52:53], v[28:29] op_sel:[0,1,0] op_sel_hi:[1,1,1]
	v_pk_mul_f32 v[86:87], v[4:5], v[64:65] op_sel:[0,1] op_sel_hi:[1,1]
	v_pk_fma_f32 v[22:23], v[6:7], v[62:63], v[22:23] op_sel:[0,0,0] op_sel_hi:[1,0,1]
	v_pk_fma_f32 v[28:29], v[6:7], v[54:55], v[28:29] op_sel:[0,0,0] op_sel_hi:[1,0,1]
	v_pk_mul_f32 v[88:89], v[6:7], v[66:67] op_sel:[0,0] op_sel_hi:[1,0]
	v_pk_fma_f32 v[22:23], v[8:9], v[62:63], v[22:23] op_sel:[0,1,0] op_sel_hi:[1,1,1]
	v_pk_fma_f32 v[28:29], v[8:9], v[54:55], v[28:29] op_sel:[0,1,0] op_sel_hi:[1,1,1]
	v_pk_mul_f32 v[90:91], v[8:9], v[66:67] op_sel:[0,1] op_sel_hi:[1,1]
	ds_read_b128 v[52:55], v20 offset:39936
	v_add_f32_dpp v24, v24, v24 row_ror:12 row_mask:0xf bank_mask:0x5
	v_add_f32_dpp v25, v25, v25 row_ror:4 row_mask:0xf bank_mask:0xa
	v_add_f32_dpp v22, v22, v22 quad_perm:[1,0,3,2] row_mask:0xf bank_mask:0xf
	v_add_f32_dpp v23, v23, v23 quad_perm:[1,0,3,2] row_mask:0xf bank_mask:0xf
	v_pk_fma_f32 v[84:85], v[72:73], v[80:81], v[84:85] op_sel:[0,0,0] op_sel_hi:[0,1,1]
	v_add_f32_dpp v26, v26, v26 row_ror:12 row_mask:0xf bank_mask:0x5
	v_add_f32_dpp v22, v22, v22 quad_perm:[2,3,0,1] row_mask:0xf bank_mask:0xf
	v_add_f32_dpp v23, v23, v23 quad_perm:[2,3,0,1] row_mask:0xf bank_mask:0xf
	v_pk_fma_f32 v[86:87], v[72:73], v[80:81], v[86:87] op_sel:[1,0,0] op_sel_hi:[1,1,1]
	v_add_f32_dpp v27, v27, v27 row_ror:4 row_mask:0xf bank_mask:0xa
	v_add_f32_dpp v22, v22, v22 row_half_mirror row_mask:0xf bank_mask:0xf
	v_add_f32_dpp v23, v23, v23 row_half_mirror row_mask:0xf bank_mask:0xf
	v_pk_fma_f32 v[88:89], v[74:75], v[80:81], v[88:89] op_sel:[0,0,0] op_sel_hi:[0,1,1]
	v_mov_b32_dpp v24, v25 quad_perm:[0,1,2,3] row_mask:0xf bank_mask:0xa
	v_add_f32_dpp v22, v22, v22 row_mirror row_mask:0xf bank_mask:0xf
	v_add_f32_dpp v23, v23, v23 row_mirror row_mask:0xf bank_mask:0xf
	v_pk_fma_f32 v[90:91], v[74:75], v[80:81], v[90:91] op_sel:[1,0,0] op_sel_hi:[1,1,1]
	v_mov_b32_dpp v26, v27 quad_perm:[0,1,2,3] row_mask:0xf bank_mask:0xa
	v_pk_fma_f32 v[2:3], v[68:69], v[22:23], v[84:85] op_sel:[0,0,0] op_sel_hi:[0,1,1] neg_lo:[1,0,0] neg_hi:[1,0,0]
	v_pk_fma_f32 v[4:5], v[68:69], v[22:23], v[86:87] op_sel:[1,0,0] op_sel_hi:[1,1,1] neg_lo:[1,0,0] neg_hi:[1,0,0]
	v_pk_fma_f32 v[6:7], v[70:71], v[22:23], v[88:89] op_sel:[0,0,0] op_sel_hi:[0,1,1] neg_lo:[1,0,0] neg_hi:[1,0,0]
	v_pk_fma_f32 v[8:9], v[70:71], v[22:23], v[90:91] op_sel:[1,0,0] op_sel_hi:[1,1,1] neg_lo:[1,0,0] neg_hi:[1,0,0]
	s_waitcnt lgkmcnt(0)
	ds_read_b128 v[60:63], v20 offset:7424
	ds_read_b128 v[64:67], v20 offset:15616
	ds_read_b64 v[80:81], v21 offset:48384
	ds_read_b128 v[72:75], v20 offset:32000
	ds_read_b128 v[68:71], v20 offset:23808
	v_pk_mul_f32 v[22:23], v[2:3], v[36:37] op_sel:[0,0] op_sel_hi:[1,0]
	v_pk_mul_f32 v[58:59], v[2:3], v[76:77] op_sel:[0,0] op_sel_hi:[1,0]
	v_pk_mul_f32 v[84:85], v[2:3], v[40:41] op_sel:[0,0] op_sel_hi:[1,0]
	v_pk_fma_f32 v[22:23], v[4:5], v[36:37], v[22:23] op_sel:[0,1,0] op_sel_hi:[1,1,1]
	v_pk_fma_f32 v[58:59], v[4:5], v[76:77], v[58:59] op_sel:[0,1,0] op_sel_hi:[1,1,1]
	v_pk_mul_f32 v[86:87], v[4:5], v[40:41] op_sel:[0,1] op_sel_hi:[1,1]
	v_pk_fma_f32 v[22:23], v[6:7], v[38:39], v[22:23] op_sel:[0,0,0] op_sel_hi:[1,0,1]
	v_pk_fma_f32 v[58:59], v[6:7], v[78:79], v[58:59] op_sel:[0,0,0] op_sel_hi:[1,0,1]
	v_pk_mul_f32 v[88:89], v[6:7], v[42:43] op_sel:[0,0] op_sel_hi:[1,0]
	v_pk_fma_f32 v[22:23], v[8:9], v[38:39], v[22:23] op_sel:[0,1,0] op_sel_hi:[1,1,1]
	v_pk_fma_f32 v[58:59], v[8:9], v[78:79], v[58:59] op_sel:[0,1,0] op_sel_hi:[1,1,1]
	v_pk_mul_f32 v[90:91], v[8:9], v[42:43] op_sel:[0,1] op_sel_hi:[1,1]
	ds_read_b128 v[76:79], v20 offset:40192
	v_add_f32_dpp v24, v24, v24 row_ror:8 row_mask:0xf bank_mask:0x3
	v_add_f32_dpp v26, v26, v26 row_ror:8 row_mask:0xf bank_mask:0xc
	v_add_f32_dpp v22, v22, v22 quad_perm:[1,0,3,2] row_mask:0xf bank_mask:0xf
	v_add_f32_dpp v23, v23, v23 quad_perm:[1,0,3,2] row_mask:0xf bank_mask:0xf
	v_pk_fma_f32 v[84:85], v[48:49], v[56:57], v[84:85] op_sel:[0,0,0] op_sel_hi:[0,1,1]
	v_mov_b32_dpp v24, v26 quad_perm:[0,1,2,3] row_mask:0xf bank_mask:0xc
	v_add_f32_dpp v22, v22, v22 quad_perm:[2,3,0,1] row_mask:0xf bank_mask:0xf
	v_add_f32_dpp v23, v23, v23 quad_perm:[2,3,0,1] row_mask:0xf bank_mask:0xf
	v_pk_fma_f32 v[86:87], v[48:49], v[56:57], v[86:87] op_sel:[1,0,0] op_sel_hi:[1,1,1]
	v_add_f32_dpp v24, v24, v24 quad_perm:[1,0,3,2] row_mask:0xf bank_mask:0xf
	v_add_f32_dpp v22, v22, v22 row_half_mirror row_mask:0xf bank_mask:0xf
	v_add_f32_dpp v23, v23, v23 row_half_mirror row_mask:0xf bank_mask:0xf
	v_pk_fma_f32 v[88:89], v[50:51], v[56:57], v[88:89] op_sel:[0,0,0] op_sel_hi:[0,1,1]
	v_add_f32_dpp v24, v24, v24 quad_perm:[2,3,0,1] row_mask:0xf bank_mask:0xf
	v_add_f32_dpp v22, v22, v22 row_mirror row_mask:0xf bank_mask:0xf
	v_add_f32_dpp v23, v23, v23 row_mirror row_mask:0xf bank_mask:0xf
	v_pk_fma_f32 v[90:91], v[50:51], v[56:57], v[90:91] op_sel:[1,0,0] op_sel_hi:[1,1,1]
	v_cndmask_b32_e64 v33, 0, v24, s[0:1]
	v_pk_fma_f32 v[2:3], v[44:45], v[22:23], v[84:85] op_sel:[0,0,0] op_sel_hi:[0,1,1] neg_lo:[1,0,0] neg_hi:[1,0,0]
	v_pk_fma_f32 v[4:5], v[44:45], v[22:23], v[86:87] op_sel:[1,0,0] op_sel_hi:[1,1,1] neg_lo:[1,0,0] neg_hi:[1,0,0]
	v_pk_fma_f32 v[6:7], v[46:47], v[22:23], v[88:89] op_sel:[0,0,0] op_sel_hi:[0,1,1] neg_lo:[1,0,0] neg_hi:[1,0,0]
	v_pk_fma_f32 v[8:9], v[46:47], v[22:23], v[90:91] op_sel:[1,0,0] op_sel_hi:[1,1,1] neg_lo:[1,0,0] neg_hi:[1,0,0]
	s_waitcnt lgkmcnt(0)
	ds_read_b128 v[36:39], v20 offset:7680
	ds_read_b128 v[40:43], v20 offset:15872
	ds_read_b64 v[56:57], v21 offset:48640
	ds_read_b128 v[48:51], v20 offset:32256
	ds_read_b128 v[44:47], v20 offset:24064
	v_pk_mul_f32 v[22:23], v[2:3], v[60:61] op_sel:[0,0] op_sel_hi:[1,0]
	v_pk_mul_f32 v[24:25], v[2:3], v[52:53] op_sel:[0,0] op_sel_hi:[1,0]
	v_pk_mul_f32 v[84:85], v[2:3], v[64:65] op_sel:[0,0] op_sel_hi:[1,0]
	v_pk_fma_f32 v[22:23], v[4:5], v[60:61], v[22:23] op_sel:[0,1,0] op_sel_hi:[1,1,1]
	v_pk_fma_f32 v[24:25], v[4:5], v[52:53], v[24:25] op_sel:[0,1,0] op_sel_hi:[1,1,1]
	v_pk_mul_f32 v[86:87], v[4:5], v[64:65] op_sel:[0,1] op_sel_hi:[1,1]
	v_pk_fma_f32 v[22:23], v[6:7], v[62:63], v[22:23] op_sel:[0,0,0] op_sel_hi:[1,0,1]
	v_pk_fma_f32 v[24:25], v[6:7], v[54:55], v[24:25] op_sel:[0,0,0] op_sel_hi:[1,0,1]
	v_pk_mul_f32 v[88:89], v[6:7], v[66:67] op_sel:[0,0] op_sel_hi:[1,0]
	v_pk_fma_f32 v[22:23], v[8:9], v[62:63], v[22:23] op_sel:[0,1,0] op_sel_hi:[1,1,1]
	v_pk_fma_f32 v[24:25], v[8:9], v[54:55], v[24:25] op_sel:[0,1,0] op_sel_hi:[1,1,1]
	v_pk_mul_f32 v[90:91], v[8:9], v[66:67] op_sel:[0,1] op_sel_hi:[1,1]
	ds_read_b128 v[52:55], v20 offset:40448
	v_add_f32_dpp v28, v28, v28 row_ror:12 row_mask:0xf bank_mask:0x5
	v_add_f32_dpp v29, v29, v29 row_ror:4 row_mask:0xf bank_mask:0xa
	v_add_f32_dpp v22, v22, v22 quad_perm:[1,0,3,2] row_mask:0xf bank_mask:0xf
	v_add_f32_dpp v23, v23, v23 quad_perm:[1,0,3,2] row_mask:0xf bank_mask:0xf
	v_pk_fma_f32 v[84:85], v[72:73], v[80:81], v[84:85] op_sel:[0,0,0] op_sel_hi:[0,1,1]
	v_add_f32_dpp v58, v58, v58 row_ror:12 row_mask:0xf bank_mask:0x5
	v_add_f32_dpp v22, v22, v22 quad_perm:[2,3,0,1] row_mask:0xf bank_mask:0xf
	v_add_f32_dpp v23, v23, v23 quad_perm:[2,3,0,1] row_mask:0xf bank_mask:0xf
	v_pk_fma_f32 v[86:87], v[72:73], v[80:81], v[86:87] op_sel:[1,0,0] op_sel_hi:[1,1,1]
	v_add_f32_dpp v59, v59, v59 row_ror:4 row_mask:0xf bank_mask:0xa
	v_add_f32_dpp v22, v22, v22 row_half_mirror row_mask:0xf bank_mask:0xf
	v_add_f32_dpp v23, v23, v23 row_half_mirror row_mask:0xf bank_mask:0xf
	v_pk_fma_f32 v[88:89], v[74:75], v[80:81], v[88:89] op_sel:[0,0,0] op_sel_hi:[0,1,1]
	v_mov_b32_dpp v28, v29 quad_perm:[0,1,2,3] row_mask:0xf bank_mask:0xa
	v_add_f32_dpp v22, v22, v22 row_mirror row_mask:0xf bank_mask:0xf
	v_add_f32_dpp v23, v23, v23 row_mirror row_mask:0xf bank_mask:0xf
	v_pk_fma_f32 v[90:91], v[74:75], v[80:81], v[90:91] op_sel:[1,0,0] op_sel_hi:[1,1,1]
	v_mov_b32_dpp v58, v59 quad_perm:[0,1,2,3] row_mask:0xf bank_mask:0xa
	v_pk_fma_f32 v[2:3], v[68:69], v[22:23], v[84:85] op_sel:[0,0,0] op_sel_hi:[0,1,1] neg_lo:[1,0,0] neg_hi:[1,0,0]
	v_pk_fma_f32 v[4:5], v[68:69], v[22:23], v[86:87] op_sel:[1,0,0] op_sel_hi:[1,1,1] neg_lo:[1,0,0] neg_hi:[1,0,0]
	v_pk_fma_f32 v[6:7], v[70:71], v[22:23], v[88:89] op_sel:[0,0,0] op_sel_hi:[0,1,1] neg_lo:[1,0,0] neg_hi:[1,0,0]
	v_pk_fma_f32 v[8:9], v[70:71], v[22:23], v[90:91] op_sel:[1,0,0] op_sel_hi:[1,1,1] neg_lo:[1,0,0] neg_hi:[1,0,0]
	s_waitcnt lgkmcnt(0)
	ds_read_b128 v[60:63], v20 offset:7936
	ds_read_b128 v[64:67], v20 offset:16128
	ds_read_b64 v[80:81], v21 offset:48896
	ds_read_b128 v[72:75], v20 offset:32512
	ds_read_b128 v[68:71], v20 offset:24320
	v_pk_mul_f32 v[22:23], v[2:3], v[36:37] op_sel:[0,0] op_sel_hi:[1,0]
	v_pk_mul_f32 v[26:27], v[2:3], v[76:77] op_sel:[0,0] op_sel_hi:[1,0]
	v_pk_mul_f32 v[84:85], v[2:3], v[40:41] op_sel:[0,0] op_sel_hi:[1,0]
	v_pk_fma_f32 v[22:23], v[4:5], v[36:37], v[22:23] op_sel:[0,1,0] op_sel_hi:[1,1,1]
	v_pk_fma_f32 v[26:27], v[4:5], v[76:77], v[26:27] op_sel:[0,1,0] op_sel_hi:[1,1,1]
	v_pk_mul_f32 v[86:87], v[4:5], v[40:41] op_sel:[0,1] op_sel_hi:[1,1]
	v_pk_fma_f32 v[22:23], v[6:7], v[38:39], v[22:23] op_sel:[0,0,0] op_sel_hi:[1,0,1]
	v_pk_fma_f32 v[26:27], v[6:7], v[78:79], v[26:27] op_sel:[0,0,0] op_sel_hi:[1,0,1]
	v_pk_mul_f32 v[88:89], v[6:7], v[42:43] op_sel:[0,0] op_sel_hi:[1,0]
	v_pk_fma_f32 v[22:23], v[8:9], v[38:39], v[22:23] op_sel:[0,1,0] op_sel_hi:[1,1,1]
	v_pk_fma_f32 v[26:27], v[8:9], v[78:79], v[26:27] op_sel:[0,1,0] op_sel_hi:[1,1,1]
	v_pk_mul_f32 v[90:91], v[8:9], v[42:43] op_sel:[0,1] op_sel_hi:[1,1]
	ds_read_b128 v[76:79], v20 offset:40704
	v_add_f32_dpp v28, v28, v28 row_ror:8 row_mask:0xf bank_mask:0x3
	v_add_f32_dpp v58, v58, v58 row_ror:8 row_mask:0xf bank_mask:0xc
	v_add_f32_dpp v22, v22, v22 quad_perm:[1,0,3,2] row_mask:0xf bank_mask:0xf
	v_add_f32_dpp v23, v23, v23 quad_perm:[1,0,3,2] row_mask:0xf bank_mask:0xf
	v_pk_fma_f32 v[84:85], v[48:49], v[56:57], v[84:85] op_sel:[0,0,0] op_sel_hi:[0,1,1]
	v_mov_b32_dpp v28, v58 quad_perm:[0,1,2,3] row_mask:0xf bank_mask:0xc
	v_add_f32_dpp v22, v22, v22 quad_perm:[2,3,0,1] row_mask:0xf bank_mask:0xf
	v_add_f32_dpp v23, v23, v23 quad_perm:[2,3,0,1] row_mask:0xf bank_mask:0xf
	v_pk_fma_f32 v[86:87], v[48:49], v[56:57], v[86:87] op_sel:[1,0,0] op_sel_hi:[1,1,1]
	v_add_f32_dpp v28, v28, v28 quad_perm:[1,0,3,2] row_mask:0xf bank_mask:0xf
	v_add_f32_dpp v22, v22, v22 row_half_mirror row_mask:0xf bank_mask:0xf
	v_add_f32_dpp v23, v23, v23 row_half_mirror row_mask:0xf bank_mask:0xf
	v_pk_fma_f32 v[88:89], v[50:51], v[56:57], v[88:89] op_sel:[0,0,0] op_sel_hi:[0,1,1]
	v_add_f32_dpp v28, v28, v28 quad_perm:[2,3,0,1] row_mask:0xf bank_mask:0xf
	v_add_f32_dpp v22, v22, v22 row_mirror row_mask:0xf bank_mask:0xf
	v_add_f32_dpp v23, v23, v23 row_mirror row_mask:0xf bank_mask:0xf
	v_pk_fma_f32 v[90:91], v[50:51], v[56:57], v[90:91] op_sel:[1,0,0] op_sel_hi:[1,1,1]
	v_cndmask_b32_e64 v33, v33, v28, s[6:7]
	v_pk_fma_f32 v[2:3], v[44:45], v[22:23], v[84:85] op_sel:[0,0,0] op_sel_hi:[0,1,1] neg_lo:[1,0,0] neg_hi:[1,0,0]
	v_pk_fma_f32 v[4:5], v[44:45], v[22:23], v[86:87] op_sel:[1,0,0] op_sel_hi:[1,1,1] neg_lo:[1,0,0] neg_hi:[1,0,0]
	v_pk_fma_f32 v[6:7], v[46:47], v[22:23], v[88:89] op_sel:[0,0,0] op_sel_hi:[0,1,1] neg_lo:[1,0,0] neg_hi:[1,0,0]
	v_pk_fma_f32 v[8:9], v[46:47], v[22:23], v[90:91] op_sel:[1,0,0] op_sel_hi:[1,1,1] neg_lo:[1,0,0] neg_hi:[1,0,0]
	s_waitcnt lgkmcnt(0)
	v_pk_mul_f32 v[22:23], v[2:3], v[60:61] op_sel:[0,0] op_sel_hi:[1,0]
	v_pk_mul_f32 v[28:29], v[2:3], v[52:53] op_sel:[0,0] op_sel_hi:[1,0]
	v_pk_mul_f32 v[84:85], v[2:3], v[64:65] op_sel:[0,0] op_sel_hi:[1,0]
	v_pk_fma_f32 v[22:23], v[4:5], v[60:61], v[22:23] op_sel:[0,1,0] op_sel_hi:[1,1,1]
	v_pk_fma_f32 v[28:29], v[4:5], v[52:53], v[28:29] op_sel:[0,1,0] op_sel_hi:[1,1,1]
	v_pk_mul_f32 v[86:87], v[4:5], v[64:65] op_sel:[0,1] op_sel_hi:[1,1]
	v_pk_fma_f32 v[22:23], v[6:7], v[62:63], v[22:23] op_sel:[0,0,0] op_sel_hi:[1,0,1]
	v_pk_fma_f32 v[28:29], v[6:7], v[54:55], v[28:29] op_sel:[0,0,0] op_sel_hi:[1,0,1]
	v_pk_mul_f32 v[88:89], v[6:7], v[66:67] op_sel:[0,0] op_sel_hi:[1,0]
	v_pk_fma_f32 v[22:23], v[8:9], v[62:63], v[22:23] op_sel:[0,1,0] op_sel_hi:[1,1,1]
	v_pk_fma_f32 v[28:29], v[8:9], v[54:55], v[28:29] op_sel:[0,1,0] op_sel_hi:[1,1,1]
	v_pk_mul_f32 v[90:91], v[8:9], v[66:67] op_sel:[0,1] op_sel_hi:[1,1]
	v_add_f32_dpp v24, v24, v24 row_ror:12 row_mask:0xf bank_mask:0x5
	v_add_f32_dpp v25, v25, v25 row_ror:4 row_mask:0xf bank_mask:0xa
	v_add_f32_dpp v22, v22, v22 quad_perm:[1,0,3,2] row_mask:0xf bank_mask:0xf
	v_add_f32_dpp v23, v23, v23 quad_perm:[1,0,3,2] row_mask:0xf bank_mask:0xf
	v_pk_fma_f32 v[84:85], v[72:73], v[80:81], v[84:85] op_sel:[0,0,0] op_sel_hi:[0,1,1]
	v_add_f32_dpp v26, v26, v26 row_ror:12 row_mask:0xf bank_mask:0x5
	v_add_f32_dpp v22, v22, v22 quad_perm:[2,3,0,1] row_mask:0xf bank_mask:0xf
	v_add_f32_dpp v23, v23, v23 quad_perm:[2,3,0,1] row_mask:0xf bank_mask:0xf
	v_pk_fma_f32 v[86:87], v[72:73], v[80:81], v[86:87] op_sel:[1,0,0] op_sel_hi:[1,1,1]
	v_add_f32_dpp v27, v27, v27 row_ror:4 row_mask:0xf bank_mask:0xa
	v_add_f32_dpp v22, v22, v22 row_half_mirror row_mask:0xf bank_mask:0xf
	v_add_f32_dpp v23, v23, v23 row_half_mirror row_mask:0xf bank_mask:0xf
	v_pk_fma_f32 v[88:89], v[74:75], v[80:81], v[88:89] op_sel:[0,0,0] op_sel_hi:[0,1,1]
	v_mov_b32_dpp v24, v25 quad_perm:[0,1,2,3] row_mask:0xf bank_mask:0xa
	v_add_f32_dpp v22, v22, v22 row_mirror row_mask:0xf bank_mask:0xf
	v_add_f32_dpp v23, v23, v23 row_mirror row_mask:0xf bank_mask:0xf
	v_pk_fma_f32 v[90:91], v[74:75], v[80:81], v[90:91] op_sel:[1,0,0] op_sel_hi:[1,1,1]
	v_mov_b32_dpp v26, v27 quad_perm:[0,1,2,3] row_mask:0xf bank_mask:0xa
	v_pk_fma_f32 v[2:3], v[68:69], v[22:23], v[84:85] op_sel:[0,0,0] op_sel_hi:[0,1,1] neg_lo:[1,0,0] neg_hi:[1,0,0]
	v_pk_fma_f32 v[4:5], v[68:69], v[22:23], v[86:87] op_sel:[1,0,0] op_sel_hi:[1,1,1] neg_lo:[1,0,0] neg_hi:[1,0,0]
	v_pk_fma_f32 v[6:7], v[70:71], v[22:23], v[88:89] op_sel:[0,0,0] op_sel_hi:[0,1,1] neg_lo:[1,0,0] neg_hi:[1,0,0]
	v_pk_fma_f32 v[8:9], v[70:71], v[22:23], v[90:91] op_sel:[1,0,0] op_sel_hi:[1,1,1] neg_lo:[1,0,0] neg_hi:[1,0,0]
	s_waitcnt lgkmcnt(0)
	v_pk_mul_f32 v[58:59], v[2:3], v[76:77] op_sel:[0,0] op_sel_hi:[1,0]
	v_pk_fma_f32 v[58:59], v[4:5], v[76:77], v[58:59] op_sel:[0,1,0] op_sel_hi:[1,1,1]
	v_pk_fma_f32 v[58:59], v[6:7], v[78:79], v[58:59] op_sel:[0,0,0] op_sel_hi:[1,0,1]
	v_pk_fma_f32 v[58:59], v[8:9], v[78:79], v[58:59] op_sel:[0,1,0] op_sel_hi:[1,1,1]
	v_add_f32_dpp v24, v24, v24 row_ror:8 row_mask:0xf bank_mask:0x3
	v_add_f32_dpp v26, v26, v26 row_ror:8 row_mask:0xf bank_mask:0xc
	s_nop 1
	v_mov_b32_dpp v24, v26 quad_perm:[0,1,2,3] row_mask:0xf bank_mask:0xc
	s_nop 1
	v_add_f32_dpp v24, v24, v24 quad_perm:[1,0,3,2] row_mask:0xf bank_mask:0xf
	s_nop 1
	v_add_f32_dpp v24, v24, v24 quad_perm:[2,3,0,1] row_mask:0xf bank_mask:0xf
	v_cndmask_b32_e64 v33, v33, v24, s[8:9]
	v_add_f32_dpp v28, v28, v28 row_ror:12 row_mask:0xf bank_mask:0x5
	v_add_f32_dpp v29, v29, v29 row_ror:4 row_mask:0xf bank_mask:0xa
	v_add_f32_dpp v58, v58, v58 row_ror:12 row_mask:0xf bank_mask:0x5
	v_add_f32_dpp v59, v59, v59 row_ror:4 row_mask:0xf bank_mask:0xa
	v_mov_b32_dpp v28, v29 quad_perm:[0,1,2,3] row_mask:0xf bank_mask:0xa
	s_nop 0
	v_mov_b32_dpp v58, v59 quad_perm:[0,1,2,3] row_mask:0xf bank_mask:0xa
	v_add_f32_dpp v28, v28, v28 row_ror:8 row_mask:0xf bank_mask:0x3
	s_nop 0
	v_add_f32_dpp v58, v58, v58 row_ror:8 row_mask:0xf bank_mask:0xc
	s_nop 1
	v_mov_b32_dpp v28, v58 quad_perm:[0,1,2,3] row_mask:0xf bank_mask:0xc
	s_nop 1
	v_add_f32_dpp v28, v28, v28 quad_perm:[1,0,3,2] row_mask:0xf bank_mask:0xf
	s_nop 1
	v_add_f32_dpp v28, v28, v28 quad_perm:[2,3,0,1] row_mask:0xf bank_mask:0xf
	v_cndmask_b32_e64 v33, v33, v28, s[10:11]
	v_lshl_add_u32 v35, s23, 12, v11
	s_add_i32 s22, s22, 1
	ds_write2st64_b32 v35, v30, v31 offset1:4
	ds_write2st64_b32 v35, v32, v33 offset0:8 offset1:12
	s_cmp_eq_u32 s22, 64
	s_waitcnt lgkmcnt(0)
	s_barrier
	s_cbranch_scc0 .LBB0_1750
	s_setprio 0
	s_lshl_b32 s0, s18, 4
	s_or_b32 s0, s0, s26
	s_ashr_i32 s1, s0, 31
	s_lshl_b64 s[0:1], s[0:1], 6
	s_lshl_b32 s2, s27, 5
	s_or_b32 s0, s0, s2
	v_or_b32_e32 v12, s0, v1
	v_mov_b32_e32 v13, s1
	v_lshlrev_b64 v[12:13], 8, v[12:13]
	v_lshl_add_u64 v[12:13], s[82:83], 0, v[12:13]
	v_mov_b32_e32 v11, 0
	v_lshl_add_u64 v[10:11], v[12:13], 0, v[10:11]
	s_mov_b64 s[0:1], 0x4100000
	v_lshl_add_u64 v[12:13], v[10:11], 0, s[0:1]
	v_add_co_u32_e32 v10, vcc, 0x4100000, v10
	s_nop 1
	v_addc_co_u32_e32 v11, vcc, 0, v11, vcc
	v_mov_b32_e32 v14, v2
	v_mov_b32_e32 v15, v4
	v_mov_b32_e32 v16, v6
	v_mov_b32_e32 v17, v8
	v_mov_b32_e32 v18, v3
	v_mov_b32_e32 v19, v5
	v_mov_b32_e32 v20, v7
	v_mov_b32_e32 v21, v9
	global_store_dwordx4 v[10:11], v[14:17], off
	global_store_dwordx4 v[12:13], v[18:21], off offset:256
